# 8-phase loops: B-half-0 fragments of the next k-tile read one phase early (8/4/8/4 reads per phase instead of 12/4/8/0)
# speedup vs baseline: 1.0166x; 1.0054x over previous
; template <bool SWAP>
; DI void gemm_mainloop(f32x16 (&acc)[4][2], const u16* __restrict__ A, int lda, int rlo, int rhi,
;                       const u16* __restrict__ B, int ldb, int K, char* lds, const u16* zero_line) {
;     ...
;   auto glds = [&](int kt, int st) {
;     char* as_ = lds + st * 65536 + tid * 16;
; #pragma unroll
;     for (int i = 0; i < 4; ++i) {
;       const int rr = lr + 64 * i;
;       const u16* srca = (rr >= rlo && rr < rhi) ? (ap + (ptrdiff_t)(64 * i) * lda + kt * 64) : (zero_line + lc * 8);
;       __builtin_amdgcn_global_load_lds((const unsigned*)srca, (lds_u32*)(as_ + i * 8192), 16, 0, 0);
;       __builtin_amdgcn_global_load_lds((const unsigned*)(bp + (ptrdiff_t)(64 * i) * ldb + kt * 64), (lds_u32*)(as_ + 32768 + i * 8192), 16, 0, 0);
;     }
;   };
;   const int sw = (r >> 1) & 7;
;   const int arow_off = (wm * 128 + r) * 128;
;   const int brow_off = 32768 + (wn * 64 + r) * 128;
;   __syncthreads();
;   glds(0, 0);
;   asm volatile("s_waitcnt vmcnt(0)" ::: "memory");
;   __syncthreads();
;   bf16x8 fa[2][4], fb[2][2];
; #pragma unroll
;   for (int mi = 0; mi < 4; ++mi)
; #pragma unroll
;     for (int e = 0; e < 8; ++e) fa[1][mi][e] = 0;
; #pragma unroll
;   for (int ni = 0; ni < 2; ++ni)
; #pragma unroll
;     for (int e = 0; e < 8; ++e) fb[1][ni][e] = 0;
;   auto ldfrag = [&](const char* st, int ks, int buf) {
;     const int co = ((2 * ks + h) ^ sw) << 4;
; #pragma unroll
;     for (int mi = 0; mi < 4; ++mi) fa[buf][mi] = *(const bf16x8*)(st + arow_off + mi * 4096 + co);
; #pragma unroll
;     for (int ni = 0; ni < 2; ++ni) fb[buf][ni] = *(const bf16x8*)(st + brow_off + ni * 4096 + co);
;   };
;   auto mma = [&](int buf) {
; #pragma unroll
;     for (int mi = 0; mi < 4; ++mi)
; #pragma unroll
;       for (int ni = 0; ni < 2; ++ni)
;         acc[mi][ni] = SWAP ? MFMA(fb[buf][ni], fa[buf][mi], acc[mi][ni]) : MFMA(fa[buf][mi], fb[buf][ni], acc[mi][ni]);
;   };
;   auto pat_rd = [&]() {
; #pragma unroll
;     for (int g = 0; g < 6; ++g) {
;       __builtin_amdgcn_sched_group_barrier(0x100, 1, 0);
;       __builtin_amdgcn_sched_group_barrier(0x008, 1, 0);
;     }
;     __builtin_amdgcn_sched_group_barrier(0x008, 2, 0);
;   };
; #pragma unroll 2
;   for (int kt = 0; kt < nk; ++kt) {
;     const char* st = lds + (kt & 1) * 65536;
;     ldfrag(st, 0, 0);
;     mma(1);
;     pat_rd();
;     if (kt + 1 < nk) glds(kt + 1, (kt + 1) & 1);
.Lg8_u0_p0:
	s_waitcnt vmcnt(4)
	s_barrier
	s_add_u32 m0, s100, 0x18000
	s_nop 0
	global_load_lds_dwordx4 v240, s[22:23]
	v_add_u32_e32 v240, 0x80, v240
	s_add_u32 m0, s100, 0x1a000
	s_nop 0
	global_load_lds_dwordx4 v242, s[22:23]
	v_add_u32_e32 v242, 0x80, v242
	s_add_u32 m0, s100, 0x10000
	s_mov_b64 exec, s[10:11]
	global_load_lds_dwordx4 v236, s[18:19]
	s_mov_b64 exec, -1
	v_add_u32_e32 v236, 0x80, v236
	s_add_u32 m0, s100, 0x12000
	s_mov_b64 exec, s[14:15]
	global_load_lds_dwordx4 v238, s[18:19]
	s_mov_b64 exec, -1
	v_add_u32_e32 v238, 0x80, v238
	s_add_u32 m0, s100, 0x1c000
	s_nop 0
	global_load_lds_dwordx4 v241, s[22:23]
	v_add_u32_e32 v241, 0x80, v241
	s_add_u32 m0, s100, 0x1e000
	s_nop 0
	global_load_lds_dwordx4 v243, s[22:23]
	v_add_u32_e32 v243, 0x80, v243
	s_waitcnt vmcnt(6)
	s_barrier
	v_add3_u32 v166, v249, v244, 0
	v_add3_u32 v167, v249, v245, 0
	v_add3_u32 v175, v249, v246, 0
	v_add3_u32 v185, v249, v247, 0
	ds_read_b128 v[176:179], v166 offset:32768
	ds_read_b128 v[180:183], v167 offset:32768
	ds_read_b128 v[186:189], v175 offset:32768
	ds_read_b128 v[190:193], v185 offset:32768
.Lg8_u0:
	v_add3_u32 v166, v248, v244, 0
	v_add3_u32 v167, v248, v245, 0
	v_add3_u32 v175, v248, v246, 0
	v_add3_u32 v185, v248, v247, 0
	ds_read_b128 v[130:133], v166
	ds_read_b128 v[134:137], v167
	ds_read_b128 v[138:141], v175
	ds_read_b128 v[142:145], v185
	ds_read_b128 v[146:149], v166 offset:4096
	ds_read_b128 v[150:153], v167 offset:4096
	ds_read_b128 v[158:161], v175 offset:4096
	ds_read_b128 v[162:165], v185 offset:4096
	s_add_u32 m0, s100, 0x14000
	s_mov_b64 exec, s[12:13]
	global_load_lds_dwordx4 v237, s[18:19]
	s_mov_b64 exec, -1
	v_add_u32_e32 v237, 0x80, v237
	s_add_u32 m0, s100, 0x16000
	s_mov_b64 exec, s[16:17]
	global_load_lds_dwordx4 v239, s[18:19]
	s_mov_b64 exec, -1
	v_add_u32_e32 v239, 0x80, v239
	s_barrier
	s_waitcnt lgkmcnt(0)
	v_mfma_f32_32x32x16_bf16 v[114:129], v[176:179], v[130:133], v[114:129]
	v_mfma_f32_32x32x16_bf16 v[82:97], v[176:179], v[146:149], v[82:97]
	v_mfma_f32_32x32x16_bf16 v[114:129], v[180:183], v[134:137], v[114:129]
	v_mfma_f32_32x32x16_bf16 v[82:97], v[180:183], v[150:153], v[82:97]
	v_mfma_f32_32x32x16_bf16 v[114:129], v[186:189], v[138:141], v[114:129]
	v_mfma_f32_32x32x16_bf16 v[82:97], v[186:189], v[158:161], v[82:97]
	v_mfma_f32_32x32x16_bf16 v[114:129], v[190:193], v[142:145], v[114:129]
	v_mfma_f32_32x32x16_bf16 v[82:97], v[190:193], v[162:165], v[82:97]
	s_barrier
	v_add3_u32 v166, v249, v244, 0
	v_add3_u32 v167, v249, v245, 0
	v_add3_u32 v175, v249, v246, 0
	v_add3_u32 v185, v249, v247, 0
	ds_read_b128 v[194:197], v166 offset:49152
	ds_read_b128 v[198:201], v167 offset:49152
	ds_read_b128 v[228:231], v175 offset:49152
	ds_read_b128 v[232:235], v185 offset:49152
	s_add_u32 m0, s100, 0x8000
	s_nop 0
	global_load_lds_dwordx4 v240, s[22:23]
	v_add_u32_e32 v240, 0x80, v240
	s_add_u32 m0, s100, 0xa000
	s_nop 0
	global_load_lds_dwordx4 v242, s[22:23]
	v_add_u32_e32 v242, 0x80, v242
	s_barrier
	s_waitcnt lgkmcnt(0)
	v_mfma_f32_32x32x16_bf16 v[98:113], v[194:197], v[130:133], v[98:113]
	v_mfma_f32_32x32x16_bf16 v[66:81], v[194:197], v[146:149], v[66:81]
	v_mfma_f32_32x32x16_bf16 v[98:113], v[198:201], v[134:137], v[98:113]
	v_mfma_f32_32x32x16_bf16 v[66:81], v[198:201], v[150:153], v[66:81]
	v_mfma_f32_32x32x16_bf16 v[98:113], v[228:231], v[138:141], v[98:113]
	v_mfma_f32_32x32x16_bf16 v[66:81], v[228:231], v[158:161], v[66:81]
	v_mfma_f32_32x32x16_bf16 v[98:113], v[232:235], v[142:145], v[98:113]
	v_mfma_f32_32x32x16_bf16 v[66:81], v[232:235], v[162:165], v[66:81]
	s_barrier
	v_add3_u32 v166, v248, v244, 0
	v_add3_u32 v167, v248, v245, 0
	v_add3_u32 v175, v248, v246, 0
	v_add3_u32 v185, v248, v247, 0
	ds_read_b128 v[130:133], v166 offset:16384
	ds_read_b128 v[134:137], v167 offset:16384
	ds_read_b128 v[138:141], v175 offset:16384
	ds_read_b128 v[142:145], v185 offset:16384
	ds_read_b128 v[146:149], v166 offset:20480
	ds_read_b128 v[150:153], v167 offset:20480
	ds_read_b128 v[158:161], v175 offset:20480
	ds_read_b128 v[162:165], v185 offset:20480
	s_add_u32 m0, s100, 0x0
	s_mov_b64 exec, s[10:11]
	global_load_lds_dwordx4 v236, s[18:19]
	s_mov_b64 exec, -1
	v_add_u32_e32 v236, 0x80, v236
	s_add_u32 m0, s100, 0x2000
	s_mov_b64 exec, s[14:15]
	global_load_lds_dwordx4 v238, s[18:19]
	s_mov_b64 exec, -1
	v_add_u32_e32 v238, 0x80, v238
	s_waitcnt vmcnt(10)
	s_barrier
	s_waitcnt lgkmcnt(0)
	v_mfma_f32_32x32x16_bf16 v[50:65], v[176:179], v[130:133], v[50:65]
	v_mfma_f32_32x32x16_bf16 v[18:33], v[176:179], v[146:149], v[18:33]
	v_mfma_f32_32x32x16_bf16 v[50:65], v[180:183], v[134:137], v[50:65]
	v_mfma_f32_32x32x16_bf16 v[18:33], v[180:183], v[150:153], v[18:33]
	v_mfma_f32_32x32x16_bf16 v[50:65], v[186:189], v[138:141], v[50:65]
	v_mfma_f32_32x32x16_bf16 v[18:33], v[186:189], v[158:161], v[18:33]
	v_mfma_f32_32x32x16_bf16 v[50:65], v[190:193], v[142:145], v[50:65]
	v_mfma_f32_32x32x16_bf16 v[18:33], v[190:193], v[162:165], v[18:33]
	s_barrier
	v_add3_u32 v166, v249, v244, s21
	v_add3_u32 v167, v249, v245, s21
	v_add3_u32 v175, v249, v246, s21
	v_add3_u32 v185, v249, v247, s21
	ds_read_b128 v[176:179], v166 offset:32768
	ds_read_b128 v[180:183], v167 offset:32768
	ds_read_b128 v[186:189], v175 offset:32768
	ds_read_b128 v[190:193], v185 offset:32768
	s_add_u32 m0, s100, 0xc000
	s_nop 0
	global_load_lds_dwordx4 v241, s[22:23]
	v_add_u32_e32 v241, 0x80, v241
	s_add_u32 m0, s100, 0xe000
	s_nop 0
	global_load_lds_dwordx4 v243, s[22:23]
	v_add_u32_e32 v243, 0x80, v243
	s_waitcnt vmcnt(6)
	s_barrier
; template <bool SWAP>
; DI void gemm_mainloop(f32x16 (&acc)[4][2], const u16* __restrict__ A, int lda, int rlo, int rhi,
;                       const u16* __restrict__ B, int ldb, int K, char* lds, const u16* zero_line) {
;     ...
; #pragma unroll 2
;   for (int kt = 0; kt < nk; ++kt) {
;     const char* st = lds + (kt & 1) * 65536;
;     ldfrag(st, 0, 0);
;     mma(1);
;     pat_rd();
;     if (kt + 1 < nk) glds(kt + 1, (kt + 1) & 1);
;     ldfrag(st, 1, 1);
;     mma(0);
;     pat_rd();
;     ldfrag(st, 2, 0);
;     mma(1);
;     pat_rd();
;     ldfrag(st, 3, 1);
;     mma(0);
;     pat_rd();
;     asm volatile("s_waitcnt vmcnt(0)" ::: "memory");
;     __syncthreads();
	s_waitcnt lgkmcnt(0)
	v_mfma_f32_32x32x16_bf16 v[34:49], v[194:197], v[130:133], v[34:49]
	v_mfma_f32_32x32x16_bf16 v[2:17], v[194:197], v[146:149], v[2:17]
	v_mfma_f32_32x32x16_bf16 v[34:49], v[198:201], v[134:137], v[34:49]
	v_mfma_f32_32x32x16_bf16 v[2:17], v[198:201], v[150:153], v[2:17]
	v_mfma_f32_32x32x16_bf16 v[34:49], v[228:231], v[138:141], v[34:49]
	v_mfma_f32_32x32x16_bf16 v[2:17], v[228:231], v[158:161], v[2:17]
	v_mfma_f32_32x32x16_bf16 v[34:49], v[232:235], v[142:145], v[34:49]
	v_mfma_f32_32x32x16_bf16 v[2:17], v[232:235], v[162:165], v[2:17]
	s_barrier
	v_add3_u32 v166, v248, v244, s21
	v_add3_u32 v167, v248, v245, s21
	v_add3_u32 v175, v248, v246, s21
	v_add3_u32 v185, v248, v247, s21
	ds_read_b128 v[130:133], v166
	ds_read_b128 v[134:137], v167
	ds_read_b128 v[138:141], v175
	ds_read_b128 v[142:145], v185
	ds_read_b128 v[146:149], v166 offset:4096
	ds_read_b128 v[150:153], v167 offset:4096
	ds_read_b128 v[158:161], v175 offset:4096
	ds_read_b128 v[162:165], v185 offset:4096
	s_add_u32 m0, s100, 0x4000
	s_mov_b64 exec, s[12:13]
	global_load_lds_dwordx4 v237, s[18:19]
	s_mov_b64 exec, -1
	v_add_u32_e32 v237, 0x80, v237
	s_add_u32 m0, s100, 0x6000
	s_mov_b64 exec, s[16:17]
	global_load_lds_dwordx4 v239, s[18:19]
	s_mov_b64 exec, -1
	v_add_u32_e32 v239, 0x80, v239
	s_barrier
	s_waitcnt lgkmcnt(0)
	v_mfma_f32_32x32x16_bf16 v[114:129], v[176:179], v[130:133], v[114:129]
	v_mfma_f32_32x32x16_bf16 v[82:97], v[176:179], v[146:149], v[82:97]
	v_mfma_f32_32x32x16_bf16 v[114:129], v[180:183], v[134:137], v[114:129]
	v_mfma_f32_32x32x16_bf16 v[82:97], v[180:183], v[150:153], v[82:97]
	v_mfma_f32_32x32x16_bf16 v[114:129], v[186:189], v[138:141], v[114:129]
	v_mfma_f32_32x32x16_bf16 v[82:97], v[186:189], v[158:161], v[82:97]
	v_mfma_f32_32x32x16_bf16 v[114:129], v[190:193], v[142:145], v[114:129]
	v_mfma_f32_32x32x16_bf16 v[82:97], v[190:193], v[162:165], v[82:97]
	s_barrier
	v_add3_u32 v166, v249, v244, s21
	v_add3_u32 v167, v249, v245, s21
	v_add3_u32 v175, v249, v246, s21
	v_add3_u32 v185, v249, v247, s21
	ds_read_b128 v[194:197], v166 offset:49152
	ds_read_b128 v[198:201], v167 offset:49152
	ds_read_b128 v[228:231], v175 offset:49152
	ds_read_b128 v[232:235], v185 offset:49152
	s_add_u32 m0, s100, 0x18000
	s_nop 0
	global_load_lds_dwordx4 v240, s[22:23]
	v_add_u32_e32 v240, 0x80, v240
	s_add_u32 m0, s100, 0x1a000
	s_nop 0
	global_load_lds_dwordx4 v242, s[22:23]
	v_add_u32_e32 v242, 0x80, v242
	s_barrier
	s_waitcnt lgkmcnt(0)
	v_mfma_f32_32x32x16_bf16 v[98:113], v[194:197], v[130:133], v[98:113]
	v_mfma_f32_32x32x16_bf16 v[66:81], v[194:197], v[146:149], v[66:81]
	v_mfma_f32_32x32x16_bf16 v[98:113], v[198:201], v[134:137], v[98:113]
	v_mfma_f32_32x32x16_bf16 v[66:81], v[198:201], v[150:153], v[66:81]
	v_mfma_f32_32x32x16_bf16 v[98:113], v[228:231], v[138:141], v[98:113]
	v_mfma_f32_32x32x16_bf16 v[66:81], v[228:231], v[158:161], v[66:81]
	v_mfma_f32_32x32x16_bf16 v[98:113], v[232:235], v[142:145], v[98:113]
	v_mfma_f32_32x32x16_bf16 v[66:81], v[232:235], v[162:165], v[66:81]
	s_barrier
	v_add3_u32 v166, v248, v244, s21
	v_add3_u32 v167, v248, v245, s21
	v_add3_u32 v175, v248, v246, s21
	v_add3_u32 v185, v248, v247, s21
	ds_read_b128 v[130:133], v166 offset:16384
	ds_read_b128 v[134:137], v167 offset:16384
	ds_read_b128 v[138:141], v175 offset:16384
	ds_read_b128 v[142:145], v185 offset:16384
	ds_read_b128 v[146:149], v166 offset:20480
	ds_read_b128 v[150:153], v167 offset:20480
	ds_read_b128 v[158:161], v175 offset:20480
	ds_read_b128 v[162:165], v185 offset:20480
	s_add_u32 m0, s100, 0x10000
	s_mov_b64 exec, s[10:11]
	global_load_lds_dwordx4 v236, s[18:19]
	s_mov_b64 exec, -1
	v_add_u32_e32 v236, 0x80, v236
	s_add_u32 m0, s100, 0x12000
	s_mov_b64 exec, s[14:15]
	global_load_lds_dwordx4 v238, s[18:19]
	s_mov_b64 exec, -1
	v_add_u32_e32 v238, 0x80, v238
	s_waitcnt vmcnt(10)
	s_barrier
	s_waitcnt lgkmcnt(0)
	v_mfma_f32_32x32x16_bf16 v[50:65], v[176:179], v[130:133], v[50:65]
	v_mfma_f32_32x32x16_bf16 v[18:33], v[176:179], v[146:149], v[18:33]
	v_mfma_f32_32x32x16_bf16 v[50:65], v[180:183], v[134:137], v[50:65]
	v_mfma_f32_32x32x16_bf16 v[18:33], v[180:183], v[150:153], v[18:33]
	v_mfma_f32_32x32x16_bf16 v[50:65], v[186:189], v[138:141], v[50:65]
	v_mfma_f32_32x32x16_bf16 v[18:33], v[186:189], v[158:161], v[18:33]
	v_mfma_f32_32x32x16_bf16 v[50:65], v[190:193], v[142:145], v[50:65]
	v_mfma_f32_32x32x16_bf16 v[18:33], v[190:193], v[162:165], v[18:33]
	s_barrier
	v_add3_u32 v166, v249, v244, 0
	v_add3_u32 v167, v249, v245, 0
	v_add3_u32 v175, v249, v246, 0
	v_add3_u32 v185, v249, v247, 0
	ds_read_b128 v[176:179], v166 offset:32768
	ds_read_b128 v[180:183], v167 offset:32768
	ds_read_b128 v[186:189], v175 offset:32768
	ds_read_b128 v[190:193], v185 offset:32768
	s_add_u32 m0, s100, 0x1c000
	s_nop 0
	global_load_lds_dwordx4 v241, s[22:23]
	v_add_u32_e32 v241, 0x80, v241
	s_add_u32 m0, s100, 0x1e000
	s_nop 0
	global_load_lds_dwordx4 v243, s[22:23]
	v_add_u32_e32 v243, 0x80, v243
	s_waitcnt vmcnt(6)
	s_barrier
	s_waitcnt lgkmcnt(0)
	v_mfma_f32_32x32x16_bf16 v[34:49], v[194:197], v[130:133], v[34:49]
	v_mfma_f32_32x32x16_bf16 v[2:17], v[194:197], v[146:149], v[2:17]
	v_mfma_f32_32x32x16_bf16 v[34:49], v[198:201], v[134:137], v[34:49]
	v_mfma_f32_32x32x16_bf16 v[2:17], v[198:201], v[150:153], v[2:17]
	v_mfma_f32_32x32x16_bf16 v[34:49], v[228:231], v[138:141], v[34:49]
	v_mfma_f32_32x32x16_bf16 v[2:17], v[228:231], v[158:161], v[2:17]
	v_mfma_f32_32x32x16_bf16 v[34:49], v[232:235], v[142:145], v[34:49]
	v_mfma_f32_32x32x16_bf16 v[2:17], v[232:235], v[162:165], v[2:17]
	s_barrier
	s_add_i32 s29, s29, 2
	s_cmp_lt_u32 s29, 14
	s_cbranch_scc1 .Lg8_u0
; template <bool SWAP>
; DI void gemm_mainloop(f32x16 (&acc)[4][2], const u16* __restrict__ A, int lda, int rlo, int rhi,
;                       const u16* __restrict__ B, int ldb, int K, char* lds, const u16* zero_line) {
;     ...
; #pragma unroll 2
;   for (int kt = 0; kt < nk; ++kt) {
;     const char* st = lds + (kt & 1) * 65536;
;     ldfrag(st, 0, 0);
;     mma(1);
;     pat_rd();
;     if (kt + 1 < nk) glds(kt + 1, (kt + 1) & 1);
;     ldfrag(st, 1, 1);
;     mma(0);
;     pat_rd();
;     ldfrag(st, 2, 0);
;     mma(1);
;     pat_rd();
;     ldfrag(st, 3, 1);
;     mma(0);
;     pat_rd();
;     asm volatile("s_waitcnt vmcnt(0)" ::: "memory");
;     __syncthreads();
;   }
;   mma(1);
	v_add3_u32 v166, v248, v244, 0
	v_add3_u32 v167, v248, v245, 0
	v_add3_u32 v175, v248, v246, 0
	v_add3_u32 v185, v248, v247, 0
	ds_read_b128 v[130:133], v166
	ds_read_b128 v[134:137], v167
	ds_read_b128 v[138:141], v175
	ds_read_b128 v[142:145], v185
	ds_read_b128 v[146:149], v166 offset:4096
	ds_read_b128 v[150:153], v167 offset:4096
	ds_read_b128 v[158:161], v175 offset:4096
	ds_read_b128 v[162:165], v185 offset:4096
	s_add_u32 m0, s100, 0x14000
	s_mov_b64 exec, s[12:13]
	global_load_lds_dwordx4 v237, s[18:19]
	s_mov_b64 exec, -1
	v_add_u32_e32 v237, 0x80, v237
	s_add_u32 m0, s100, 0x16000
	s_mov_b64 exec, s[16:17]
	global_load_lds_dwordx4 v239, s[18:19]
	s_mov_b64 exec, -1
	v_add_u32_e32 v239, 0x80, v239
	s_barrier
	s_waitcnt lgkmcnt(0)
	v_mfma_f32_32x32x16_bf16 v[114:129], v[176:179], v[130:133], v[114:129]
	v_mfma_f32_32x32x16_bf16 v[82:97], v[176:179], v[146:149], v[82:97]
	v_mfma_f32_32x32x16_bf16 v[114:129], v[180:183], v[134:137], v[114:129]
	v_mfma_f32_32x32x16_bf16 v[82:97], v[180:183], v[150:153], v[82:97]
	v_mfma_f32_32x32x16_bf16 v[114:129], v[186:189], v[138:141], v[114:129]
	v_mfma_f32_32x32x16_bf16 v[82:97], v[186:189], v[158:161], v[82:97]
	v_mfma_f32_32x32x16_bf16 v[114:129], v[190:193], v[142:145], v[114:129]
	v_mfma_f32_32x32x16_bf16 v[82:97], v[190:193], v[162:165], v[82:97]
	s_barrier
	v_add3_u32 v166, v249, v244, 0
	v_add3_u32 v167, v249, v245, 0
	v_add3_u32 v175, v249, v246, 0
	v_add3_u32 v185, v249, v247, 0
	ds_read_b128 v[194:197], v166 offset:49152
	ds_read_b128 v[198:201], v167 offset:49152
	ds_read_b128 v[228:231], v175 offset:49152
	ds_read_b128 v[232:235], v185 offset:49152
	s_barrier
	s_waitcnt lgkmcnt(0)
	v_mfma_f32_32x32x16_bf16 v[98:113], v[194:197], v[130:133], v[98:113]
	v_mfma_f32_32x32x16_bf16 v[66:81], v[194:197], v[146:149], v[66:81]
	v_mfma_f32_32x32x16_bf16 v[98:113], v[198:201], v[134:137], v[98:113]
	v_mfma_f32_32x32x16_bf16 v[66:81], v[198:201], v[150:153], v[66:81]
	v_mfma_f32_32x32x16_bf16 v[98:113], v[228:231], v[138:141], v[98:113]
	v_mfma_f32_32x32x16_bf16 v[66:81], v[228:231], v[158:161], v[66:81]
	v_mfma_f32_32x32x16_bf16 v[98:113], v[232:235], v[142:145], v[98:113]
	v_mfma_f32_32x32x16_bf16 v[66:81], v[232:235], v[162:165], v[66:81]
	s_barrier
	v_add3_u32 v166, v248, v244, 0
	v_add3_u32 v167, v248, v245, 0
	v_add3_u32 v175, v248, v246, 0
	v_add3_u32 v185, v248, v247, 0
	ds_read_b128 v[130:133], v166 offset:16384
	ds_read_b128 v[134:137], v167 offset:16384
	ds_read_b128 v[138:141], v175 offset:16384
	ds_read_b128 v[142:145], v185 offset:16384
	ds_read_b128 v[146:149], v166 offset:20480
	ds_read_b128 v[150:153], v167 offset:20480
	ds_read_b128 v[158:161], v175 offset:20480
	ds_read_b128 v[162:165], v185 offset:20480
	s_waitcnt vmcnt(4)
	s_barrier
	s_waitcnt lgkmcnt(0)
	v_mfma_f32_32x32x16_bf16 v[50:65], v[176:179], v[130:133], v[50:65]
	v_mfma_f32_32x32x16_bf16 v[18:33], v[176:179], v[146:149], v[18:33]
	v_mfma_f32_32x32x16_bf16 v[50:65], v[180:183], v[134:137], v[50:65]
	v_mfma_f32_32x32x16_bf16 v[18:33], v[180:183], v[150:153], v[18:33]
	v_mfma_f32_32x32x16_bf16 v[50:65], v[186:189], v[138:141], v[50:65]
	v_mfma_f32_32x32x16_bf16 v[18:33], v[186:189], v[158:161], v[18:33]
	v_mfma_f32_32x32x16_bf16 v[50:65], v[190:193], v[142:145], v[50:65]
	v_mfma_f32_32x32x16_bf16 v[18:33], v[190:193], v[162:165], v[18:33]
	v_mfma_f32_32x32x16_bf16 v[34:49], v[194:197], v[130:133], v[34:49]
	v_mfma_f32_32x32x16_bf16 v[2:17], v[194:197], v[146:149], v[2:17]
	v_mfma_f32_32x32x16_bf16 v[34:49], v[198:201], v[134:137], v[34:49]
	v_mfma_f32_32x32x16_bf16 v[2:17], v[198:201], v[150:153], v[2:17]
	v_mfma_f32_32x32x16_bf16 v[34:49], v[228:231], v[138:141], v[34:49]
	v_mfma_f32_32x32x16_bf16 v[2:17], v[228:231], v[158:161], v[2:17]
	v_mfma_f32_32x32x16_bf16 v[34:49], v[232:235], v[142:145], v[34:49]
	v_mfma_f32_32x32x16_bf16 v[2:17], v[232:235], v[162:165], v[2:17]
	s_barrier
; template <bool SWAP>
; DI void gemm_mainloop(f32x16 (&acc)[4][2], const u16* __restrict__ A, int lda, int rlo, int rhi,
;                       const u16* __restrict__ B, int ldb, int K, char* lds, const u16* zero_line) {
;     ...
; #pragma unroll 2
;   for (int kt = 0; kt < nk; ++kt) {
;     const char* st = lds + (kt & 1) * 65536;
;     ldfrag(st, 0, 0);
;     mma(1);
;     pat_rd();
;     if (kt + 1 < nk) glds(kt + 1, (kt + 1) & 1);
;     ldfrag(st, 1, 1);
;     mma(0);
;     pat_rd();
;     ldfrag(st, 2, 0);
;     mma(1);
;     pat_rd();
;     ldfrag(st, 3, 1);
;     mma(0);
;     pat_rd();
;     asm volatile("s_waitcnt vmcnt(0)" ::: "memory");
;     __syncthreads();
;   }
;   mma(1);
	v_add3_u32 v166, v249, v244, s21
	v_add3_u32 v167, v249, v245, s21
	v_add3_u32 v175, v249, v246, s21
	v_add3_u32 v185, v249, v247, s21
	ds_read_b128 v[176:179], v166 offset:32768
	ds_read_b128 v[180:183], v167 offset:32768
	ds_read_b128 v[186:189], v175 offset:32768
	ds_read_b128 v[190:193], v185 offset:32768
	v_add3_u32 v166, v248, v244, s21
	v_add3_u32 v167, v248, v245, s21
	v_add3_u32 v175, v248, v246, s21
	v_add3_u32 v185, v248, v247, s21
	ds_read_b128 v[130:133], v166
	ds_read_b128 v[134:137], v167
	ds_read_b128 v[138:141], v175
	ds_read_b128 v[142:145], v185
	ds_read_b128 v[146:149], v166 offset:4096
	ds_read_b128 v[150:153], v167 offset:4096
	ds_read_b128 v[158:161], v175 offset:4096
	ds_read_b128 v[162:165], v185 offset:4096
	s_waitcnt vmcnt(2)
	s_barrier
	s_waitcnt lgkmcnt(0)
	v_mfma_f32_32x32x16_bf16 v[114:129], v[176:179], v[130:133], v[114:129]
	v_mfma_f32_32x32x16_bf16 v[82:97], v[176:179], v[146:149], v[82:97]
	v_mfma_f32_32x32x16_bf16 v[114:129], v[180:183], v[134:137], v[114:129]
	v_mfma_f32_32x32x16_bf16 v[82:97], v[180:183], v[150:153], v[82:97]
	v_mfma_f32_32x32x16_bf16 v[114:129], v[186:189], v[138:141], v[114:129]
	v_mfma_f32_32x32x16_bf16 v[82:97], v[186:189], v[158:161], v[82:97]
	v_mfma_f32_32x32x16_bf16 v[114:129], v[190:193], v[142:145], v[114:129]
	v_mfma_f32_32x32x16_bf16 v[82:97], v[190:193], v[162:165], v[82:97]
	s_barrier
	v_add3_u32 v166, v249, v244, s21
	v_add3_u32 v167, v249, v245, s21
	v_add3_u32 v175, v249, v246, s21
	v_add3_u32 v185, v249, v247, s21
	ds_read_b128 v[194:197], v166 offset:49152
	ds_read_b128 v[198:201], v167 offset:49152
	ds_read_b128 v[228:231], v175 offset:49152
	ds_read_b128 v[232:235], v185 offset:49152
	s_waitcnt vmcnt(0)
	s_barrier
	s_waitcnt lgkmcnt(0)
	v_mfma_f32_32x32x16_bf16 v[98:113], v[194:197], v[130:133], v[98:113]
	v_mfma_f32_32x32x16_bf16 v[66:81], v[194:197], v[146:149], v[66:81]
	v_mfma_f32_32x32x16_bf16 v[98:113], v[198:201], v[134:137], v[98:113]
	v_mfma_f32_32x32x16_bf16 v[66:81], v[198:201], v[150:153], v[66:81]
	v_mfma_f32_32x32x16_bf16 v[98:113], v[228:231], v[138:141], v[98:113]
	v_mfma_f32_32x32x16_bf16 v[66:81], v[228:231], v[158:161], v[66:81]
	v_mfma_f32_32x32x16_bf16 v[98:113], v[232:235], v[142:145], v[98:113]
	v_mfma_f32_32x32x16_bf16 v[66:81], v[232:235], v[162:165], v[66:81]
	s_barrier
	v_add3_u32 v166, v248, v244, s21
	v_add3_u32 v167, v248, v245, s21
	v_add3_u32 v175, v248, v246, s21
	v_add3_u32 v185, v248, v247, s21
	ds_read_b128 v[130:133], v166 offset:16384
	ds_read_b128 v[134:137], v167 offset:16384
	ds_read_b128 v[138:141], v175 offset:16384
	ds_read_b128 v[142:145], v185 offset:16384
	ds_read_b128 v[146:149], v166 offset:20480
	ds_read_b128 v[150:153], v167 offset:20480
	ds_read_b128 v[158:161], v175 offset:20480
	ds_read_b128 v[162:165], v185 offset:20480
	s_barrier
	s_waitcnt lgkmcnt(0)
	v_mfma_f32_32x32x16_bf16 v[50:65], v[176:179], v[130:133], v[50:65]
	v_mfma_f32_32x32x16_bf16 v[18:33], v[176:179], v[146:149], v[18:33]
	v_mfma_f32_32x32x16_bf16 v[50:65], v[180:183], v[134:137], v[50:65]
	v_mfma_f32_32x32x16_bf16 v[18:33], v[180:183], v[150:153], v[18:33]
	v_mfma_f32_32x32x16_bf16 v[50:65], v[186:189], v[138:141], v[50:65]
	v_mfma_f32_32x32x16_bf16 v[18:33], v[186:189], v[158:161], v[18:33]
	v_mfma_f32_32x32x16_bf16 v[50:65], v[190:193], v[142:145], v[50:65]
	v_mfma_f32_32x32x16_bf16 v[18:33], v[190:193], v[162:165], v[18:33]
	v_mfma_f32_32x32x16_bf16 v[34:49], v[194:197], v[130:133], v[34:49]
	v_mfma_f32_32x32x16_bf16 v[2:17], v[194:197], v[146:149], v[2:17]
	v_mfma_f32_32x32x16_bf16 v[34:49], v[198:201], v[134:137], v[34:49]
	v_mfma_f32_32x32x16_bf16 v[2:17], v[198:201], v[150:153], v[2:17]
	v_mfma_f32_32x32x16_bf16 v[34:49], v[228:231], v[138:141], v[34:49]
	v_mfma_f32_32x32x16_bf16 v[2:17], v[228:231], v[158:161], v[2:17]
	v_mfma_f32_32x32x16_bf16 v[34:49], v[232:235], v[142:145], v[34:49]
	v_mfma_f32_32x32x16_bf16 v[2:17], v[232:235], v[162:165], v[2:17]
	s_barrier
	s_cmp_eq_u32 s101, 0
	s_cbranch_scc0 .Lg8_u0_p1
	s_barrier

; template <bool SWAP>
; DI void gemm_mainloop(f32x16 (&acc)[4][2], const u16* __restrict__ A, int lda, int rlo, int rhi,
;                       const u16* __restrict__ B, int ldb, int K, char* lds, const u16* zero_line) {
;     ...
;   auto glds = [&](int kt, int st) {
;     char* as_ = lds + st * 65536 + tid * 16;
; #pragma unroll
;     for (int i = 0; i < 4; ++i) {
;       const int rr = lr + 64 * i;
;       const u16* srca = (rr >= rlo && rr < rhi) ? (ap + (ptrdiff_t)(64 * i) * lda + kt * 64) : (zero_line + lc * 8);
;       __builtin_amdgcn_global_load_lds((const unsigned*)srca, (lds_u32*)(as_ + i * 8192), 16, 0, 0);
;       __builtin_amdgcn_global_load_lds((const unsigned*)(bp + (ptrdiff_t)(64 * i) * ldb + kt * 64), (lds_u32*)(as_ + 32768 + i * 8192), 16, 0, 0);
;     }
;   };
;   const int sw = (r >> 1) & 7;
;   const int arow_off = (wm * 128 + r) * 128;
;   const int brow_off = 32768 + (wn * 64 + r) * 128;
;   __syncthreads();
;   glds(0, 0);
;   asm volatile("s_waitcnt vmcnt(0)" ::: "memory");
;   __syncthreads();
;   bf16x8 fa[2][4], fb[2][2];
; #pragma unroll
;   for (int mi = 0; mi < 4; ++mi)
; #pragma unroll
;     for (int e = 0; e < 8; ++e) fa[1][mi][e] = 0;
; #pragma unroll
;   for (int ni = 0; ni < 2; ++ni)
; #pragma unroll
;     for (int e = 0; e < 8; ++e) fb[1][ni][e] = 0;
;   auto ldfrag = [&](const char* st, int ks, int buf) {
;     const int co = ((2 * ks + h) ^ sw) << 4;
; #pragma unroll
;     for (int mi = 0; mi < 4; ++mi) fa[buf][mi] = *(const bf16x8*)(st + arow_off + mi * 4096 + co);
; #pragma unroll
;     for (int ni = 0; ni < 2; ++ni) fb[buf][ni] = *(const bf16x8*)(st + brow_off + ni * 4096 + co);
;   };
;   auto mma = [&](int buf) {
; #pragma unroll
;     for (int mi = 0; mi < 4; ++mi)
; #pragma unroll
;       for (int ni = 0; ni < 2; ++ni)
;         acc[mi][ni] = SWAP ? MFMA(fb[buf][ni], fa[buf][mi], acc[mi][ni]) : MFMA(fa[buf][mi], fb[buf][ni], acc[mi][ni]);
;   };
;   auto pat_rd = [&]() {
; #pragma unroll
;     for (int g = 0; g < 6; ++g) {
;       __builtin_amdgcn_sched_group_barrier(0x100, 1, 0);
;       __builtin_amdgcn_sched_group_barrier(0x008, 1, 0);
;     }
;     __builtin_amdgcn_sched_group_barrier(0x008, 2, 0);
;   };
; #pragma unroll 2
;   for (int kt = 0; kt < nk; ++kt) {
;     const char* st = lds + (kt & 1) * 65536;
;     ldfrag(st, 0, 0);
;     mma(1);
;     pat_rd();
;     if (kt + 1 < nk) glds(kt + 1, (kt + 1) & 1);
.Lg8_qa_p0:
	s_waitcnt vmcnt(4)
	s_barrier
	s_add_u32 m0, s100, 0x18000
	s_nop 0
	global_load_lds_dwordx4 v236, s[8:9]
	v_add_u32_e32 v236, 0x80, v236
	s_add_u32 m0, s100, 0x1a000
	s_nop 0
	global_load_lds_dwordx4 v238, s[8:9]
	v_add_u32_e32 v238, 0x80, v238
	s_add_u32 m0, s100, 0x10000
	s_nop 0
	global_load_lds_dwordx4 v232, s[6:7]
	v_add_u32_e32 v232, 0x80, v232
	s_add_u32 m0, s100, 0x12000
	s_nop 0
	global_load_lds_dwordx4 v234, s[6:7]
	v_add_u32_e32 v234, 0x80, v234
	s_add_u32 m0, s100, 0x1c000
	s_nop 0
	global_load_lds_dwordx4 v237, s[8:9]
	v_add_u32_e32 v237, 0x80, v237
	s_add_u32 m0, s100, 0x1e000
	s_nop 0
	global_load_lds_dwordx4 v239, s[8:9]
	v_add_u32_e32 v239, 0x80, v239
	s_waitcnt vmcnt(6)
	s_barrier
	v_add3_u32 v246, v245, v240, 0
	v_add3_u32 v247, v245, v241, 0
	v_add3_u32 v248, v245, v242, 0
	v_add3_u32 v249, v245, v243, 0
	ds_read_b128 v[170:173], v246 offset:32768
	ds_read_b128 v[174:177], v247 offset:32768
	ds_read_b128 v[178:181], v248 offset:32768
	ds_read_b128 v[186:189], v249 offset:32768
.Lg8_qa:
	v_add3_u32 v246, v244, v240, 0
	v_add3_u32 v247, v244, v241, 0
	v_add3_u32 v248, v244, v242, 0
	v_add3_u32 v249, v244, v243, 0
	ds_read_b128 v[130:133], v246
	ds_read_b128 v[134:137], v247
	ds_read_b128 v[138:141], v248
	ds_read_b128 v[142:145], v249
	ds_read_b128 v[146:149], v246 offset:4096
	ds_read_b128 v[150:153], v247 offset:4096
	ds_read_b128 v[156:159], v248 offset:4096
	ds_read_b128 v[160:163], v249 offset:4096
	s_add_u32 m0, s100, 0x14000
	s_nop 0
	global_load_lds_dwordx4 v233, s[6:7]
	v_add_u32_e32 v233, 0x80, v233
	s_add_u32 m0, s100, 0x16000
	s_nop 0
	global_load_lds_dwordx4 v235, s[6:7]
	v_add_u32_e32 v235, 0x80, v235
	s_barrier
	s_waitcnt lgkmcnt(0)
	v_mfma_f32_32x32x16_bf16 v[114:129], v[130:133], v[170:173], v[114:129]
	v_mfma_f32_32x32x16_bf16 v[82:97], v[146:149], v[170:173], v[82:97]
	v_mfma_f32_32x32x16_bf16 v[114:129], v[134:137], v[174:177], v[114:129]
	v_mfma_f32_32x32x16_bf16 v[82:97], v[150:153], v[174:177], v[82:97]
	v_mfma_f32_32x32x16_bf16 v[114:129], v[138:141], v[178:181], v[114:129]
	v_mfma_f32_32x32x16_bf16 v[82:97], v[156:159], v[178:181], v[82:97]
	v_mfma_f32_32x32x16_bf16 v[114:129], v[142:145], v[186:189], v[114:129]
	v_mfma_f32_32x32x16_bf16 v[82:97], v[160:163], v[186:189], v[82:97]
	s_barrier
	v_add3_u32 v246, v245, v240, 0
	v_add3_u32 v247, v245, v241, 0
	v_add3_u32 v248, v245, v242, 0
	v_add3_u32 v249, v245, v243, 0
	ds_read_b128 v[190:193], v246 offset:49152
	ds_read_b128 v[194:197], v247 offset:49152
	ds_read_b128 v[198:201], v248 offset:49152
	ds_read_b128 v[228:231], v249 offset:49152
	s_add_u32 m0, s100, 0x8000
	s_nop 0
	global_load_lds_dwordx4 v236, s[8:9]
	v_add_u32_e32 v236, 0x80, v236
	s_add_u32 m0, s100, 0xa000
	s_nop 0
	global_load_lds_dwordx4 v238, s[8:9]
	v_add_u32_e32 v238, 0x80, v238
	s_barrier
	s_waitcnt lgkmcnt(0)
	v_mfma_f32_32x32x16_bf16 v[98:113], v[130:133], v[190:193], v[98:113]
	v_mfma_f32_32x32x16_bf16 v[66:81], v[146:149], v[190:193], v[66:81]
	v_mfma_f32_32x32x16_bf16 v[98:113], v[134:137], v[194:197], v[98:113]
	v_mfma_f32_32x32x16_bf16 v[66:81], v[150:153], v[194:197], v[66:81]
	v_mfma_f32_32x32x16_bf16 v[98:113], v[138:141], v[198:201], v[98:113]
	v_mfma_f32_32x32x16_bf16 v[66:81], v[156:159], v[198:201], v[66:81]
	v_mfma_f32_32x32x16_bf16 v[98:113], v[142:145], v[228:231], v[98:113]
	v_mfma_f32_32x32x16_bf16 v[66:81], v[160:163], v[228:231], v[66:81]
	s_barrier
	v_add3_u32 v246, v244, v240, 0
	v_add3_u32 v247, v244, v241, 0
	v_add3_u32 v248, v244, v242, 0
	v_add3_u32 v249, v244, v243, 0
	ds_read_b128 v[130:133], v246 offset:16384
	ds_read_b128 v[134:137], v247 offset:16384
	ds_read_b128 v[138:141], v248 offset:16384
	ds_read_b128 v[142:145], v249 offset:16384
	ds_read_b128 v[146:149], v246 offset:20480
	ds_read_b128 v[150:153], v247 offset:20480
	ds_read_b128 v[156:159], v248 offset:20480
	ds_read_b128 v[160:163], v249 offset:20480
	s_add_u32 m0, s100, 0x0
	s_nop 0
	global_load_lds_dwordx4 v232, s[6:7]
	v_add_u32_e32 v232, 0x80, v232
	s_add_u32 m0, s100, 0x2000
	s_nop 0
	global_load_lds_dwordx4 v234, s[6:7]
	v_add_u32_e32 v234, 0x80, v234
	s_waitcnt vmcnt(10)
	s_barrier
	s_waitcnt lgkmcnt(0)
	v_mfma_f32_32x32x16_bf16 v[50:65], v[130:133], v[170:173], v[50:65]
	v_mfma_f32_32x32x16_bf16 v[18:33], v[146:149], v[170:173], v[18:33]
	v_mfma_f32_32x32x16_bf16 v[50:65], v[134:137], v[174:177], v[50:65]
	v_mfma_f32_32x32x16_bf16 v[18:33], v[150:153], v[174:177], v[18:33]
	v_mfma_f32_32x32x16_bf16 v[50:65], v[138:141], v[178:181], v[50:65]
	v_mfma_f32_32x32x16_bf16 v[18:33], v[156:159], v[178:181], v[18:33]
	v_mfma_f32_32x32x16_bf16 v[50:65], v[142:145], v[186:189], v[50:65]
	v_mfma_f32_32x32x16_bf16 v[18:33], v[160:163], v[186:189], v[18:33]
	s_barrier
	v_add3_u32 v246, v245, v240, s10
	v_add3_u32 v247, v245, v241, s10
	v_add3_u32 v248, v245, v242, s10
	v_add3_u32 v249, v245, v243, s10
	ds_read_b128 v[170:173], v246 offset:32768
	ds_read_b128 v[174:177], v247 offset:32768
	ds_read_b128 v[178:181], v248 offset:32768
	ds_read_b128 v[186:189], v249 offset:32768
	s_add_u32 m0, s100, 0xc000
	s_nop 0
	global_load_lds_dwordx4 v237, s[8:9]
	v_add_u32_e32 v237, 0x80, v237
	s_add_u32 m0, s100, 0xe000
	s_nop 0
	global_load_lds_dwordx4 v239, s[8:9]
	v_add_u32_e32 v239, 0x80, v239
	s_waitcnt vmcnt(6)
	s_barrier
	s_waitcnt lgkmcnt(0)
	v_mfma_f32_32x32x16_bf16 v[34:49], v[130:133], v[190:193], v[34:49]
	v_mfma_f32_32x32x16_bf16 v[2:17], v[146:149], v[190:193], v[2:17]
	v_mfma_f32_32x32x16_bf16 v[34:49], v[134:137], v[194:197], v[34:49]
	v_mfma_f32_32x32x16_bf16 v[2:17], v[150:153], v[194:197], v[2:17]
	v_mfma_f32_32x32x16_bf16 v[34:49], v[138:141], v[198:201], v[34:49]
	v_mfma_f32_32x32x16_bf16 v[2:17], v[156:159], v[198:201], v[2:17]
	v_mfma_f32_32x32x16_bf16 v[34:49], v[142:145], v[228:231], v[34:49]
	v_mfma_f32_32x32x16_bf16 v[2:17], v[160:163], v[228:231], v[2:17]
	s_barrier
; template <bool SWAP>
; DI void gemm_mainloop(f32x16 (&acc)[4][2], const u16* __restrict__ A, int lda, int rlo, int rhi,
;                       const u16* __restrict__ B, int ldb, int K, char* lds, const u16* zero_line) {
;     ...
; #pragma unroll 2
;   for (int kt = 0; kt < nk; ++kt) {
;     const char* st = lds + (kt & 1) * 65536;
;     ldfrag(st, 0, 0);
;     mma(1);
;     pat_rd();
;     if (kt + 1 < nk) glds(kt + 1, (kt + 1) & 1);
;     ldfrag(st, 1, 1);
;     mma(0);
;     pat_rd();
;     ldfrag(st, 2, 0);
;     mma(1);
;     pat_rd();
;     ldfrag(st, 3, 1);
;     mma(0);
;     pat_rd();
;     asm volatile("s_waitcnt vmcnt(0)" ::: "memory");
;     __syncthreads();
;   }
;   mma(1);
	v_add3_u32 v246, v244, v240, s10
	v_add3_u32 v247, v244, v241, s10
	v_add3_u32 v248, v244, v242, s10
	v_add3_u32 v249, v244, v243, s10
	ds_read_b128 v[130:133], v246
	ds_read_b128 v[134:137], v247
	ds_read_b128 v[138:141], v248
	ds_read_b128 v[142:145], v249
	ds_read_b128 v[146:149], v246 offset:4096
	ds_read_b128 v[150:153], v247 offset:4096
	ds_read_b128 v[156:159], v248 offset:4096
	ds_read_b128 v[160:163], v249 offset:4096
	s_add_u32 m0, s100, 0x4000
	s_nop 0
	global_load_lds_dwordx4 v233, s[6:7]
	v_add_u32_e32 v233, 0x80, v233
	s_add_u32 m0, s100, 0x6000
	s_nop 0
	global_load_lds_dwordx4 v235, s[6:7]
	v_add_u32_e32 v235, 0x80, v235
	s_barrier
	s_waitcnt lgkmcnt(0)
	v_mfma_f32_32x32x16_bf16 v[114:129], v[130:133], v[170:173], v[114:129]
	v_mfma_f32_32x32x16_bf16 v[82:97], v[146:149], v[170:173], v[82:97]
	v_mfma_f32_32x32x16_bf16 v[114:129], v[134:137], v[174:177], v[114:129]
	v_mfma_f32_32x32x16_bf16 v[82:97], v[150:153], v[174:177], v[82:97]
	v_mfma_f32_32x32x16_bf16 v[114:129], v[138:141], v[178:181], v[114:129]
	v_mfma_f32_32x32x16_bf16 v[82:97], v[156:159], v[178:181], v[82:97]
	v_mfma_f32_32x32x16_bf16 v[114:129], v[142:145], v[186:189], v[114:129]
	v_mfma_f32_32x32x16_bf16 v[82:97], v[160:163], v[186:189], v[82:97]
	s_barrier
	v_add3_u32 v246, v245, v240, s10
	v_add3_u32 v247, v245, v241, s10
	v_add3_u32 v248, v245, v242, s10
	v_add3_u32 v249, v245, v243, s10
	ds_read_b128 v[190:193], v246 offset:49152
	ds_read_b128 v[194:197], v247 offset:49152
	ds_read_b128 v[198:201], v248 offset:49152
	ds_read_b128 v[228:231], v249 offset:49152
	s_add_u32 m0, s100, 0x18000
	s_nop 0
	global_load_lds_dwordx4 v236, s[8:9]
	v_add_u32_e32 v236, 0x80, v236
	s_add_u32 m0, s100, 0x1a000
	s_nop 0
	global_load_lds_dwordx4 v238, s[8:9]
	v_add_u32_e32 v238, 0x80, v238
	s_barrier
	s_waitcnt lgkmcnt(0)
	v_mfma_f32_32x32x16_bf16 v[98:113], v[130:133], v[190:193], v[98:113]
	v_mfma_f32_32x32x16_bf16 v[66:81], v[146:149], v[190:193], v[66:81]
	v_mfma_f32_32x32x16_bf16 v[98:113], v[134:137], v[194:197], v[98:113]
	v_mfma_f32_32x32x16_bf16 v[66:81], v[150:153], v[194:197], v[66:81]
	v_mfma_f32_32x32x16_bf16 v[98:113], v[138:141], v[198:201], v[98:113]
	v_mfma_f32_32x32x16_bf16 v[66:81], v[156:159], v[198:201], v[66:81]
	v_mfma_f32_32x32x16_bf16 v[98:113], v[142:145], v[228:231], v[98:113]
	v_mfma_f32_32x32x16_bf16 v[66:81], v[160:163], v[228:231], v[66:81]
	s_barrier
	v_add3_u32 v246, v244, v240, s10
	v_add3_u32 v247, v244, v241, s10
	v_add3_u32 v248, v244, v242, s10
	v_add3_u32 v249, v244, v243, s10
	ds_read_b128 v[130:133], v246 offset:16384
	ds_read_b128 v[134:137], v247 offset:16384
	ds_read_b128 v[138:141], v248 offset:16384
	ds_read_b128 v[142:145], v249 offset:16384
	ds_read_b128 v[146:149], v246 offset:20480
	ds_read_b128 v[150:153], v247 offset:20480
	ds_read_b128 v[156:159], v248 offset:20480
	ds_read_b128 v[160:163], v249 offset:20480
	s_add_u32 m0, s100, 0x10000
	s_nop 0
	global_load_lds_dwordx4 v232, s[6:7]
	v_add_u32_e32 v232, 0x80, v232
	s_add_u32 m0, s100, 0x12000
	s_nop 0
	global_load_lds_dwordx4 v234, s[6:7]
	v_add_u32_e32 v234, 0x80, v234
	s_waitcnt vmcnt(10)
	s_barrier
	s_waitcnt lgkmcnt(0)
	v_mfma_f32_32x32x16_bf16 v[50:65], v[130:133], v[170:173], v[50:65]
	v_mfma_f32_32x32x16_bf16 v[18:33], v[146:149], v[170:173], v[18:33]
	v_mfma_f32_32x32x16_bf16 v[50:65], v[134:137], v[174:177], v[50:65]
	v_mfma_f32_32x32x16_bf16 v[18:33], v[150:153], v[174:177], v[18:33]
	v_mfma_f32_32x32x16_bf16 v[50:65], v[138:141], v[178:181], v[50:65]
	v_mfma_f32_32x32x16_bf16 v[18:33], v[156:159], v[178:181], v[18:33]
	v_mfma_f32_32x32x16_bf16 v[50:65], v[142:145], v[186:189], v[50:65]
	v_mfma_f32_32x32x16_bf16 v[18:33], v[160:163], v[186:189], v[18:33]
	s_barrier
	v_add3_u32 v246, v245, v240, 0
	v_add3_u32 v247, v245, v241, 0
	v_add3_u32 v248, v245, v242, 0
	v_add3_u32 v249, v245, v243, 0
	ds_read_b128 v[170:173], v246 offset:32768
	ds_read_b128 v[174:177], v247 offset:32768
	ds_read_b128 v[178:181], v248 offset:32768
	ds_read_b128 v[186:189], v249 offset:32768
	s_add_u32 m0, s100, 0x1c000
	s_nop 0
	global_load_lds_dwordx4 v237, s[8:9]
	v_add_u32_e32 v237, 0x80, v237
	s_add_u32 m0, s100, 0x1e000
	s_nop 0
	global_load_lds_dwordx4 v239, s[8:9]
	v_add_u32_e32 v239, 0x80, v239
	s_waitcnt vmcnt(6)
	s_barrier
	s_waitcnt lgkmcnt(0)
	v_mfma_f32_32x32x16_bf16 v[34:49], v[130:133], v[190:193], v[34:49]
	v_mfma_f32_32x32x16_bf16 v[2:17], v[146:149], v[190:193], v[2:17]
	v_mfma_f32_32x32x16_bf16 v[34:49], v[134:137], v[194:197], v[34:49]
	v_mfma_f32_32x32x16_bf16 v[2:17], v[150:153], v[194:197], v[2:17]
	v_mfma_f32_32x32x16_bf16 v[34:49], v[138:141], v[198:201], v[34:49]
	v_mfma_f32_32x32x16_bf16 v[2:17], v[156:159], v[198:201], v[2:17]
	v_mfma_f32_32x32x16_bf16 v[34:49], v[142:145], v[228:231], v[34:49]
	v_mfma_f32_32x32x16_bf16 v[2:17], v[160:163], v[228:231], v[2:17]
	s_barrier
	s_add_i32 s11, s11, 2
	s_cmp_lt_u32 s11, 14
	s_cbranch_scc1 .Lg8_qa
	v_add3_u32 v246, v244, v240, 0
	v_add3_u32 v247, v244, v241, 0
	v_add3_u32 v248, v244, v242, 0
	v_add3_u32 v249, v244, v243, 0
	ds_read_b128 v[130:133], v246
	ds_read_b128 v[134:137], v247
	ds_read_b128 v[138:141], v248
	ds_read_b128 v[142:145], v249
	ds_read_b128 v[146:149], v246 offset:4096
	ds_read_b128 v[150:153], v247 offset:4096
	ds_read_b128 v[156:159], v248 offset:4096
	ds_read_b128 v[160:163], v249 offset:4096
	s_add_u32 m0, s100, 0x14000
	s_nop 0
	global_load_lds_dwordx4 v233, s[6:7]
	v_add_u32_e32 v233, 0x80, v233
	s_add_u32 m0, s100, 0x16000
	s_nop 0
	global_load_lds_dwordx4 v235, s[6:7]
	v_add_u32_e32 v235, 0x80, v235
	s_barrier
; template <bool SWAP>
; DI void gemm_mainloop(f32x16 (&acc)[4][2], const u16* __restrict__ A, int lda, int rlo, int rhi,
;                       const u16* __restrict__ B, int ldb, int K, char* lds, const u16* zero_line) {
;     ...
; #pragma unroll 2
;   for (int kt = 0; kt < nk; ++kt) {
;     const char* st = lds + (kt & 1) * 65536;
;     ldfrag(st, 0, 0);
;     mma(1);
;     pat_rd();
;     if (kt + 1 < nk) glds(kt + 1, (kt + 1) & 1);
;     ldfrag(st, 1, 1);
;     mma(0);
;     pat_rd();
;     ldfrag(st, 2, 0);
;     mma(1);
;     pat_rd();
;     ldfrag(st, 3, 1);
;     mma(0);
;     pat_rd();
;     asm volatile("s_waitcnt vmcnt(0)" ::: "memory");
;     __syncthreads();
;   }
;   mma(1);
	s_waitcnt lgkmcnt(0)
	v_mfma_f32_32x32x16_bf16 v[114:129], v[130:133], v[170:173], v[114:129]
	v_mfma_f32_32x32x16_bf16 v[82:97], v[146:149], v[170:173], v[82:97]
	v_mfma_f32_32x32x16_bf16 v[114:129], v[134:137], v[174:177], v[114:129]
	v_mfma_f32_32x32x16_bf16 v[82:97], v[150:153], v[174:177], v[82:97]
	v_mfma_f32_32x32x16_bf16 v[114:129], v[138:141], v[178:181], v[114:129]
	v_mfma_f32_32x32x16_bf16 v[82:97], v[156:159], v[178:181], v[82:97]
	v_mfma_f32_32x32x16_bf16 v[114:129], v[142:145], v[186:189], v[114:129]
	v_mfma_f32_32x32x16_bf16 v[82:97], v[160:163], v[186:189], v[82:97]
	s_barrier
	v_add3_u32 v246, v245, v240, 0
	v_add3_u32 v247, v245, v241, 0
	v_add3_u32 v248, v245, v242, 0
	v_add3_u32 v249, v245, v243, 0
	ds_read_b128 v[190:193], v246 offset:49152
	ds_read_b128 v[194:197], v247 offset:49152
	ds_read_b128 v[198:201], v248 offset:49152
	ds_read_b128 v[228:231], v249 offset:49152
	s_barrier
	s_waitcnt lgkmcnt(0)
	v_mfma_f32_32x32x16_bf16 v[98:113], v[130:133], v[190:193], v[98:113]
	v_mfma_f32_32x32x16_bf16 v[66:81], v[146:149], v[190:193], v[66:81]
	v_mfma_f32_32x32x16_bf16 v[98:113], v[134:137], v[194:197], v[98:113]
	v_mfma_f32_32x32x16_bf16 v[66:81], v[150:153], v[194:197], v[66:81]
	v_mfma_f32_32x32x16_bf16 v[98:113], v[138:141], v[198:201], v[98:113]
	v_mfma_f32_32x32x16_bf16 v[66:81], v[156:159], v[198:201], v[66:81]
	v_mfma_f32_32x32x16_bf16 v[98:113], v[142:145], v[228:231], v[98:113]
	v_mfma_f32_32x32x16_bf16 v[66:81], v[160:163], v[228:231], v[66:81]
	s_barrier
	v_add3_u32 v246, v244, v240, 0
	v_add3_u32 v247, v244, v241, 0
	v_add3_u32 v248, v244, v242, 0
	v_add3_u32 v249, v244, v243, 0
	ds_read_b128 v[130:133], v246 offset:16384
	ds_read_b128 v[134:137], v247 offset:16384
	ds_read_b128 v[138:141], v248 offset:16384
	ds_read_b128 v[142:145], v249 offset:16384
	ds_read_b128 v[146:149], v246 offset:20480
	ds_read_b128 v[150:153], v247 offset:20480
	ds_read_b128 v[156:159], v248 offset:20480
	ds_read_b128 v[160:163], v249 offset:20480
	s_waitcnt vmcnt(4)
	s_barrier
	s_waitcnt lgkmcnt(0)
	v_mfma_f32_32x32x16_bf16 v[50:65], v[130:133], v[170:173], v[50:65]
	v_mfma_f32_32x32x16_bf16 v[18:33], v[146:149], v[170:173], v[18:33]
	v_mfma_f32_32x32x16_bf16 v[50:65], v[134:137], v[174:177], v[50:65]
	v_mfma_f32_32x32x16_bf16 v[18:33], v[150:153], v[174:177], v[18:33]
	v_mfma_f32_32x32x16_bf16 v[50:65], v[138:141], v[178:181], v[50:65]
	v_mfma_f32_32x32x16_bf16 v[18:33], v[156:159], v[178:181], v[18:33]
	v_mfma_f32_32x32x16_bf16 v[50:65], v[142:145], v[186:189], v[50:65]
	v_mfma_f32_32x32x16_bf16 v[18:33], v[160:163], v[186:189], v[18:33]
	v_mfma_f32_32x32x16_bf16 v[34:49], v[130:133], v[190:193], v[34:49]
	v_mfma_f32_32x32x16_bf16 v[2:17], v[146:149], v[190:193], v[2:17]
	v_mfma_f32_32x32x16_bf16 v[34:49], v[134:137], v[194:197], v[34:49]
	v_mfma_f32_32x32x16_bf16 v[2:17], v[150:153], v[194:197], v[2:17]
	v_mfma_f32_32x32x16_bf16 v[34:49], v[138:141], v[198:201], v[34:49]
	v_mfma_f32_32x32x16_bf16 v[2:17], v[156:159], v[198:201], v[2:17]
	v_mfma_f32_32x32x16_bf16 v[34:49], v[142:145], v[228:231], v[34:49]
	v_mfma_f32_32x32x16_bf16 v[2:17], v[160:163], v[228:231], v[2:17]
	s_barrier
	v_add3_u32 v246, v245, v240, s10
	v_add3_u32 v247, v245, v241, s10
	v_add3_u32 v248, v245, v242, s10
	v_add3_u32 v249, v245, v243, s10
	ds_read_b128 v[170:173], v246 offset:32768
	ds_read_b128 v[174:177], v247 offset:32768
	ds_read_b128 v[178:181], v248 offset:32768
	ds_read_b128 v[186:189], v249 offset:32768
	v_add3_u32 v246, v244, v240, s10
	v_add3_u32 v247, v244, v241, s10
	v_add3_u32 v248, v244, v242, s10
	v_add3_u32 v249, v244, v243, s10
	ds_read_b128 v[130:133], v246
	ds_read_b128 v[134:137], v247
	ds_read_b128 v[138:141], v248
	ds_read_b128 v[142:145], v249
	ds_read_b128 v[146:149], v246 offset:4096
	ds_read_b128 v[150:153], v247 offset:4096
	ds_read_b128 v[156:159], v248 offset:4096
	ds_read_b128 v[160:163], v249 offset:4096
	s_waitcnt vmcnt(2)
	s_barrier
; template <bool SWAP>
; DI void gemm_mainloop(f32x16 (&acc)[4][2], const u16* __restrict__ A, int lda, int rlo, int rhi,
;                       const u16* __restrict__ B, int ldb, int K, char* lds, const u16* zero_line) {
;     ...
;     ldfrag(st, 2, 0);
;     mma(1);
;     pat_rd();
;     ldfrag(st, 3, 1);
;     mma(0);
;     pat_rd();
;     asm volatile("s_waitcnt vmcnt(0)" ::: "memory");
;     __syncthreads();
;   }
;   mma(1);
	s_waitcnt lgkmcnt(0)
	v_mfma_f32_32x32x16_bf16 v[114:129], v[130:133], v[170:173], v[114:129]
	v_mfma_f32_32x32x16_bf16 v[82:97], v[146:149], v[170:173], v[82:97]
	v_mfma_f32_32x32x16_bf16 v[114:129], v[134:137], v[174:177], v[114:129]
	v_mfma_f32_32x32x16_bf16 v[82:97], v[150:153], v[174:177], v[82:97]
	v_mfma_f32_32x32x16_bf16 v[114:129], v[138:141], v[178:181], v[114:129]
	v_mfma_f32_32x32x16_bf16 v[82:97], v[156:159], v[178:181], v[82:97]
	v_mfma_f32_32x32x16_bf16 v[114:129], v[142:145], v[186:189], v[114:129]
	v_mfma_f32_32x32x16_bf16 v[82:97], v[160:163], v[186:189], v[82:97]
	s_barrier
	v_add3_u32 v246, v245, v240, s10
	v_add3_u32 v247, v245, v241, s10
	v_add3_u32 v248, v245, v242, s10
	v_add3_u32 v249, v245, v243, s10
	ds_read_b128 v[190:193], v246 offset:49152
	ds_read_b128 v[194:197], v247 offset:49152
	ds_read_b128 v[198:201], v248 offset:49152
	ds_read_b128 v[228:231], v249 offset:49152
	s_waitcnt vmcnt(0)
	s_barrier
	s_waitcnt lgkmcnt(0)
	v_mfma_f32_32x32x16_bf16 v[98:113], v[130:133], v[190:193], v[98:113]
	v_mfma_f32_32x32x16_bf16 v[66:81], v[146:149], v[190:193], v[66:81]
	v_mfma_f32_32x32x16_bf16 v[98:113], v[134:137], v[194:197], v[98:113]
	v_mfma_f32_32x32x16_bf16 v[66:81], v[150:153], v[194:197], v[66:81]
	v_mfma_f32_32x32x16_bf16 v[98:113], v[138:141], v[198:201], v[98:113]
	v_mfma_f32_32x32x16_bf16 v[66:81], v[156:159], v[198:201], v[66:81]
	v_mfma_f32_32x32x16_bf16 v[98:113], v[142:145], v[228:231], v[98:113]
	v_mfma_f32_32x32x16_bf16 v[66:81], v[160:163], v[228:231], v[66:81]
	s_barrier
	v_add3_u32 v246, v244, v240, s10
	v_add3_u32 v247, v244, v241, s10
	v_add3_u32 v248, v244, v242, s10
	v_add3_u32 v249, v244, v243, s10
	ds_read_b128 v[130:133], v246 offset:16384
	ds_read_b128 v[134:137], v247 offset:16384
	ds_read_b128 v[138:141], v248 offset:16384
	ds_read_b128 v[142:145], v249 offset:16384
	ds_read_b128 v[146:149], v246 offset:20480
	ds_read_b128 v[150:153], v247 offset:20480
	ds_read_b128 v[156:159], v248 offset:20480
	ds_read_b128 v[160:163], v249 offset:20480
	s_barrier
	s_waitcnt lgkmcnt(0)
	v_mfma_f32_32x32x16_bf16 v[50:65], v[130:133], v[170:173], v[50:65]
	v_mfma_f32_32x32x16_bf16 v[18:33], v[146:149], v[170:173], v[18:33]
	v_mfma_f32_32x32x16_bf16 v[50:65], v[134:137], v[174:177], v[50:65]
	v_mfma_f32_32x32x16_bf16 v[18:33], v[150:153], v[174:177], v[18:33]
	v_mfma_f32_32x32x16_bf16 v[50:65], v[138:141], v[178:181], v[50:65]
	v_mfma_f32_32x32x16_bf16 v[18:33], v[156:159], v[178:181], v[18:33]
	v_mfma_f32_32x32x16_bf16 v[50:65], v[142:145], v[186:189], v[50:65]
	v_mfma_f32_32x32x16_bf16 v[18:33], v[160:163], v[186:189], v[18:33]
	v_mfma_f32_32x32x16_bf16 v[34:49], v[130:133], v[190:193], v[34:49]
	v_mfma_f32_32x32x16_bf16 v[2:17], v[146:149], v[190:193], v[2:17]
	v_mfma_f32_32x32x16_bf16 v[34:49], v[134:137], v[194:197], v[34:49]
	v_mfma_f32_32x32x16_bf16 v[2:17], v[150:153], v[194:197], v[2:17]
	v_mfma_f32_32x32x16_bf16 v[34:49], v[138:141], v[198:201], v[34:49]
	v_mfma_f32_32x32x16_bf16 v[2:17], v[156:159], v[198:201], v[2:17]
	v_mfma_f32_32x32x16_bf16 v[34:49], v[142:145], v[228:231], v[34:49]
	v_mfma_f32_32x32x16_bf16 v[2:17], v[160:163], v[228:231], v[2:17]
	s_barrier
	s_cmp_eq_u32 s101, 0
	s_cbranch_scc0 .Lg8_qa_p1
	s_barrier

; template <bool SWAP>
; DI void gemm_mainloop(f32x16 (&acc)[4][2], const u16* __restrict__ A, int lda, int rlo, int rhi,
;                       const u16* __restrict__ B, int ldb, int K, char* lds, const u16* zero_line) {
;     ...
; #pragma unroll 2
;   for (int kt = 0; kt < nk; ++kt) {
;     const char* st = lds + (kt & 1) * 65536;
;     ldfrag(st, 0, 0);
;     mma(1);
;     pat_rd();
;     if (kt + 1 < nk) glds(kt + 1, (kt + 1) & 1);
;     ldfrag(st, 1, 1);
;     mma(0);
;     pat_rd();
;     ldfrag(st, 2, 0);
;     mma(1);
;     pat_rd();
;     ldfrag(st, 3, 1);
;     mma(0);
;     pat_rd();
;     asm volatile("s_waitcnt vmcnt(0)" ::: "memory");
;     __syncthreads();
.Lg8_qb:
	v_add3_u32 v246, v244, v240, 0
	v_add3_u32 v247, v244, v241, 0
	v_add3_u32 v248, v244, v242, 0
	v_add3_u32 v249, v244, v243, 0
	ds_read_b128 v[130:133], v246
	ds_read_b128 v[134:137], v247
	ds_read_b128 v[138:141], v248
	ds_read_b128 v[142:145], v249
	ds_read_b128 v[146:149], v246 offset:4096
	ds_read_b128 v[150:153], v247 offset:4096
	ds_read_b128 v[156:159], v248 offset:4096
	ds_read_b128 v[160:163], v249 offset:4096
	s_add_u32 m0, s100, 0x14000
	s_nop 0
	global_load_lds_dwordx4 v233, s[6:7]
	v_add_u32_e32 v233, 0x80, v233
	s_add_u32 m0, s100, 0x16000
	s_nop 0
	global_load_lds_dwordx4 v235, s[6:7]
	v_add_u32_e32 v235, 0x80, v235
	s_barrier
	s_waitcnt lgkmcnt(0)
	v_mfma_f32_32x32x16_bf16 v[114:129], v[170:173], v[130:133], v[114:129]
	v_mfma_f32_32x32x16_bf16 v[82:97], v[170:173], v[146:149], v[82:97]
	v_mfma_f32_32x32x16_bf16 v[114:129], v[174:177], v[134:137], v[114:129]
	v_mfma_f32_32x32x16_bf16 v[82:97], v[174:177], v[150:153], v[82:97]
	v_mfma_f32_32x32x16_bf16 v[114:129], v[178:181], v[138:141], v[114:129]
	v_mfma_f32_32x32x16_bf16 v[82:97], v[178:181], v[156:159], v[82:97]
	v_mfma_f32_32x32x16_bf16 v[114:129], v[186:189], v[142:145], v[114:129]
	v_mfma_f32_32x32x16_bf16 v[82:97], v[186:189], v[160:163], v[82:97]
	s_barrier
	v_add3_u32 v246, v245, v240, 0
	v_add3_u32 v247, v245, v241, 0
	v_add3_u32 v248, v245, v242, 0
	v_add3_u32 v249, v245, v243, 0
	ds_read_b128 v[190:193], v246 offset:49152
	ds_read_b128 v[194:197], v247 offset:49152
	ds_read_b128 v[198:201], v248 offset:49152
	ds_read_b128 v[228:231], v249 offset:49152
	s_add_u32 m0, s100, 0x8000
	s_nop 0
	global_load_lds_dwordx4 v236, s[8:9]
	v_add_u32_e32 v236, 0x80, v236
	s_add_u32 m0, s100, 0xa000
	s_nop 0
	global_load_lds_dwordx4 v238, s[8:9]
	v_add_u32_e32 v238, 0x80, v238
	s_barrier
	s_waitcnt lgkmcnt(0)
	v_mfma_f32_32x32x16_bf16 v[98:113], v[190:193], v[130:133], v[98:113]
	v_mfma_f32_32x32x16_bf16 v[66:81], v[190:193], v[146:149], v[66:81]
	v_mfma_f32_32x32x16_bf16 v[98:113], v[194:197], v[134:137], v[98:113]
	v_mfma_f32_32x32x16_bf16 v[66:81], v[194:197], v[150:153], v[66:81]
	v_mfma_f32_32x32x16_bf16 v[98:113], v[198:201], v[138:141], v[98:113]
	v_mfma_f32_32x32x16_bf16 v[66:81], v[198:201], v[156:159], v[66:81]
	v_mfma_f32_32x32x16_bf16 v[98:113], v[228:231], v[142:145], v[98:113]
	v_mfma_f32_32x32x16_bf16 v[66:81], v[228:231], v[160:163], v[66:81]
	s_barrier
	v_add3_u32 v246, v244, v240, 0
	v_add3_u32 v247, v244, v241, 0
	v_add3_u32 v248, v244, v242, 0
	v_add3_u32 v249, v244, v243, 0
	ds_read_b128 v[130:133], v246 offset:16384
	ds_read_b128 v[134:137], v247 offset:16384
	ds_read_b128 v[138:141], v248 offset:16384
	ds_read_b128 v[142:145], v249 offset:16384
	ds_read_b128 v[146:149], v246 offset:20480
	ds_read_b128 v[150:153], v247 offset:20480
	ds_read_b128 v[156:159], v248 offset:20480
	ds_read_b128 v[160:163], v249 offset:20480
	s_add_u32 m0, s100, 0x0
	s_nop 0
	global_load_lds_dwordx4 v232, s[6:7]
	v_add_u32_e32 v232, 0x80, v232
	s_add_u32 m0, s100, 0x2000
	s_nop 0
	global_load_lds_dwordx4 v234, s[6:7]
	v_add_u32_e32 v234, 0x80, v234
	s_waitcnt vmcnt(10)
	s_barrier
	s_waitcnt lgkmcnt(0)
	v_mfma_f32_32x32x16_bf16 v[50:65], v[170:173], v[130:133], v[50:65]
	v_mfma_f32_32x32x16_bf16 v[18:33], v[170:173], v[146:149], v[18:33]
	v_mfma_f32_32x32x16_bf16 v[50:65], v[174:177], v[134:137], v[50:65]
	v_mfma_f32_32x32x16_bf16 v[18:33], v[174:177], v[150:153], v[18:33]
	v_mfma_f32_32x32x16_bf16 v[50:65], v[178:181], v[138:141], v[50:65]
	v_mfma_f32_32x32x16_bf16 v[18:33], v[178:181], v[156:159], v[18:33]
	v_mfma_f32_32x32x16_bf16 v[50:65], v[186:189], v[142:145], v[50:65]
	v_mfma_f32_32x32x16_bf16 v[18:33], v[186:189], v[160:163], v[18:33]
	s_barrier
	v_add3_u32 v246, v245, v240, s10
	v_add3_u32 v247, v245, v241, s10
	v_add3_u32 v248, v245, v242, s10
	v_add3_u32 v249, v245, v243, s10
	ds_read_b128 v[170:173], v246 offset:32768
	ds_read_b128 v[174:177], v247 offset:32768
	ds_read_b128 v[178:181], v248 offset:32768
	ds_read_b128 v[186:189], v249 offset:32768
	s_add_u32 m0, s100, 0xc000
	s_nop 0
	global_load_lds_dwordx4 v237, s[8:9]
	v_add_u32_e32 v237, 0x80, v237
	s_add_u32 m0, s100, 0xe000
	s_nop 0
	global_load_lds_dwordx4 v239, s[8:9]
	v_add_u32_e32 v239, 0x80, v239
	s_waitcnt vmcnt(6)
	s_barrier
	s_waitcnt lgkmcnt(0)
	v_mfma_f32_32x32x16_bf16 v[34:49], v[190:193], v[130:133], v[34:49]
	v_mfma_f32_32x32x16_bf16 v[2:17], v[190:193], v[146:149], v[2:17]
	v_mfma_f32_32x32x16_bf16 v[34:49], v[194:197], v[134:137], v[34:49]
	v_mfma_f32_32x32x16_bf16 v[2:17], v[194:197], v[150:153], v[2:17]
	v_mfma_f32_32x32x16_bf16 v[34:49], v[198:201], v[138:141], v[34:49]
	v_mfma_f32_32x32x16_bf16 v[2:17], v[198:201], v[156:159], v[2:17]
	v_mfma_f32_32x32x16_bf16 v[34:49], v[228:231], v[142:145], v[34:49]
	v_mfma_f32_32x32x16_bf16 v[2:17], v[228:231], v[160:163], v[2:17]
	s_barrier
	v_add3_u32 v246, v244, v240, s10
	v_add3_u32 v247, v244, v241, s10
	v_add3_u32 v248, v244, v242, s10
	v_add3_u32 v249, v244, v243, s10
	ds_read_b128 v[130:133], v246
	ds_read_b128 v[134:137], v247
	ds_read_b128 v[138:141], v248
	ds_read_b128 v[142:145], v249
	ds_read_b128 v[146:149], v246 offset:4096
	ds_read_b128 v[150:153], v247 offset:4096
	ds_read_b128 v[156:159], v248 offset:4096
	ds_read_b128 v[160:163], v249 offset:4096
	s_add_u32 m0, s100, 0x4000
	s_nop 0
	global_load_lds_dwordx4 v233, s[6:7]
	v_add_u32_e32 v233, 0x80, v233
	s_add_u32 m0, s100, 0x6000
	s_nop 0
	global_load_lds_dwordx4 v235, s[6:7]
	v_add_u32_e32 v235, 0x80, v235
	s_barrier
; template <bool SWAP>
; DI void gemm_mainloop(f32x16 (&acc)[4][2], const u16* __restrict__ A, int lda, int rlo, int rhi,
;                       const u16* __restrict__ B, int ldb, int K, char* lds, const u16* zero_line) {
;     ...
;   for (int kt = 0; kt < nk; ++kt) {
;     const char* st = lds + (kt & 1) * 65536;
;     ldfrag(st, 0, 0);
;     mma(1);
;     pat_rd();
;     if (kt + 1 < nk) glds(kt + 1, (kt + 1) & 1);
;     ldfrag(st, 1, 1);
;     mma(0);
;     pat_rd();
;     ldfrag(st, 2, 0);
;     mma(1);
;     pat_rd();
;     ldfrag(st, 3, 1);
;     mma(0);
;     pat_rd();
;     asm volatile("s_waitcnt vmcnt(0)" ::: "memory");
;     __syncthreads();
;   }
	s_waitcnt lgkmcnt(0)
	v_mfma_f32_32x32x16_bf16 v[114:129], v[170:173], v[130:133], v[114:129]
	v_mfma_f32_32x32x16_bf16 v[82:97], v[170:173], v[146:149], v[82:97]
	v_mfma_f32_32x32x16_bf16 v[114:129], v[174:177], v[134:137], v[114:129]
	v_mfma_f32_32x32x16_bf16 v[82:97], v[174:177], v[150:153], v[82:97]
	v_mfma_f32_32x32x16_bf16 v[114:129], v[178:181], v[138:141], v[114:129]
	v_mfma_f32_32x32x16_bf16 v[82:97], v[178:181], v[156:159], v[82:97]
	v_mfma_f32_32x32x16_bf16 v[114:129], v[186:189], v[142:145], v[114:129]
	v_mfma_f32_32x32x16_bf16 v[82:97], v[186:189], v[160:163], v[82:97]
	s_barrier
	v_add3_u32 v246, v245, v240, s10
	v_add3_u32 v247, v245, v241, s10
	v_add3_u32 v248, v245, v242, s10
	v_add3_u32 v249, v245, v243, s10
	ds_read_b128 v[190:193], v246 offset:49152
	ds_read_b128 v[194:197], v247 offset:49152
	ds_read_b128 v[198:201], v248 offset:49152
	ds_read_b128 v[228:231], v249 offset:49152
	s_add_u32 m0, s100, 0x18000
	s_nop 0
	global_load_lds_dwordx4 v236, s[8:9]
	v_add_u32_e32 v236, 0x80, v236
	s_add_u32 m0, s100, 0x1a000
	s_nop 0
	global_load_lds_dwordx4 v238, s[8:9]
	v_add_u32_e32 v238, 0x80, v238
	s_barrier
	s_waitcnt lgkmcnt(0)
	v_mfma_f32_32x32x16_bf16 v[98:113], v[190:193], v[130:133], v[98:113]
	v_mfma_f32_32x32x16_bf16 v[66:81], v[190:193], v[146:149], v[66:81]
	v_mfma_f32_32x32x16_bf16 v[98:113], v[194:197], v[134:137], v[98:113]
	v_mfma_f32_32x32x16_bf16 v[66:81], v[194:197], v[150:153], v[66:81]
	v_mfma_f32_32x32x16_bf16 v[98:113], v[198:201], v[138:141], v[98:113]
	v_mfma_f32_32x32x16_bf16 v[66:81], v[198:201], v[156:159], v[66:81]
	v_mfma_f32_32x32x16_bf16 v[98:113], v[228:231], v[142:145], v[98:113]
	v_mfma_f32_32x32x16_bf16 v[66:81], v[228:231], v[160:163], v[66:81]
	s_barrier
	v_add3_u32 v246, v244, v240, s10
	v_add3_u32 v247, v244, v241, s10
	v_add3_u32 v248, v244, v242, s10
	v_add3_u32 v249, v244, v243, s10
	ds_read_b128 v[130:133], v246 offset:16384
	ds_read_b128 v[134:137], v247 offset:16384
	ds_read_b128 v[138:141], v248 offset:16384
	ds_read_b128 v[142:145], v249 offset:16384
	ds_read_b128 v[146:149], v246 offset:20480
	ds_read_b128 v[150:153], v247 offset:20480
	ds_read_b128 v[156:159], v248 offset:20480
	ds_read_b128 v[160:163], v249 offset:20480
	s_add_u32 m0, s100, 0x10000
	s_nop 0
	global_load_lds_dwordx4 v232, s[6:7]
	v_add_u32_e32 v232, 0x80, v232
	s_add_u32 m0, s100, 0x12000
	s_nop 0
	global_load_lds_dwordx4 v234, s[6:7]
	v_add_u32_e32 v234, 0x80, v234
	s_waitcnt vmcnt(10)
	s_barrier
	s_waitcnt lgkmcnt(0)
	v_mfma_f32_32x32x16_bf16 v[50:65], v[170:173], v[130:133], v[50:65]
	v_mfma_f32_32x32x16_bf16 v[18:33], v[170:173], v[146:149], v[18:33]
	v_mfma_f32_32x32x16_bf16 v[50:65], v[174:177], v[134:137], v[50:65]
	v_mfma_f32_32x32x16_bf16 v[18:33], v[174:177], v[150:153], v[18:33]
	v_mfma_f32_32x32x16_bf16 v[50:65], v[178:181], v[138:141], v[50:65]
	v_mfma_f32_32x32x16_bf16 v[18:33], v[178:181], v[156:159], v[18:33]
	v_mfma_f32_32x32x16_bf16 v[50:65], v[186:189], v[142:145], v[50:65]
	v_mfma_f32_32x32x16_bf16 v[18:33], v[186:189], v[160:163], v[18:33]
	s_barrier
	v_add3_u32 v246, v245, v240, 0
	v_add3_u32 v247, v245, v241, 0
	v_add3_u32 v248, v245, v242, 0
	v_add3_u32 v249, v245, v243, 0
	ds_read_b128 v[170:173], v246 offset:32768
	ds_read_b128 v[174:177], v247 offset:32768
	ds_read_b128 v[178:181], v248 offset:32768
	ds_read_b128 v[186:189], v249 offset:32768
	s_add_u32 m0, s100, 0x1c000
	s_nop 0
	global_load_lds_dwordx4 v237, s[8:9]
	v_add_u32_e32 v237, 0x80, v237
	s_add_u32 m0, s100, 0x1e000
	s_nop 0
	global_load_lds_dwordx4 v239, s[8:9]
	v_add_u32_e32 v239, 0x80, v239
	s_waitcnt vmcnt(6)
	s_barrier
	s_waitcnt lgkmcnt(0)
	v_mfma_f32_32x32x16_bf16 v[34:49], v[190:193], v[130:133], v[34:49]
	v_mfma_f32_32x32x16_bf16 v[2:17], v[190:193], v[146:149], v[2:17]
	v_mfma_f32_32x32x16_bf16 v[34:49], v[194:197], v[134:137], v[34:49]
	v_mfma_f32_32x32x16_bf16 v[2:17], v[194:197], v[150:153], v[2:17]
	v_mfma_f32_32x32x16_bf16 v[34:49], v[198:201], v[138:141], v[34:49]
	v_mfma_f32_32x32x16_bf16 v[2:17], v[198:201], v[156:159], v[2:17]
	v_mfma_f32_32x32x16_bf16 v[34:49], v[228:231], v[142:145], v[34:49]
	v_mfma_f32_32x32x16_bf16 v[2:17], v[228:231], v[160:163], v[2:17]
	s_barrier
	s_add_i32 s11, s11, 2
	s_cmp_lt_u32 s11, 14
	s_cbranch_scc1 .Lg8_qb
	v_add3_u32 v246, v244, v240, 0
	v_add3_u32 v247, v244, v241, 0
	v_add3_u32 v248, v244, v242, 0
	v_add3_u32 v249, v244, v243, 0
	ds_read_b128 v[130:133], v246
	ds_read_b128 v[134:137], v247
	ds_read_b128 v[138:141], v248
	ds_read_b128 v[142:145], v249
	ds_read_b128 v[146:149], v246 offset:4096
	ds_read_b128 v[150:153], v247 offset:4096
	ds_read_b128 v[156:159], v248 offset:4096
	ds_read_b128 v[160:163], v249 offset:4096
	s_add_u32 m0, s100, 0x14000
	s_nop 0
	global_load_lds_dwordx4 v233, s[6:7]
	v_add_u32_e32 v233, 0x80, v233
	s_add_u32 m0, s100, 0x16000
	s_nop 0
	global_load_lds_dwordx4 v235, s[6:7]
	v_add_u32_e32 v235, 0x80, v235
	s_barrier
	s_waitcnt lgkmcnt(0)
	v_mfma_f32_32x32x16_bf16 v[114:129], v[170:173], v[130:133], v[114:129]
	v_mfma_f32_32x32x16_bf16 v[82:97], v[170:173], v[146:149], v[82:97]
	v_mfma_f32_32x32x16_bf16 v[114:129], v[174:177], v[134:137], v[114:129]
	v_mfma_f32_32x32x16_bf16 v[82:97], v[174:177], v[150:153], v[82:97]
	v_mfma_f32_32x32x16_bf16 v[114:129], v[178:181], v[138:141], v[114:129]
	v_mfma_f32_32x32x16_bf16 v[82:97], v[178:181], v[156:159], v[82:97]
	v_mfma_f32_32x32x16_bf16 v[114:129], v[186:189], v[142:145], v[114:129]
	v_mfma_f32_32x32x16_bf16 v[82:97], v[186:189], v[160:163], v[82:97]
	s_barrier
; template <bool SWAP>
; DI void gemm_mainloop(f32x16 (&acc)[4][2], const u16* __restrict__ A, int lda, int rlo, int rhi,
;                       const u16* __restrict__ B, int ldb, int K, char* lds, const u16* zero_line) {
;     ...
;   for (int kt = 0; kt < nk; ++kt) {
;     const char* st = lds + (kt & 1) * 65536;
;     ldfrag(st, 0, 0);
;     mma(1);
;     pat_rd();
;     if (kt + 1 < nk) glds(kt + 1, (kt + 1) & 1);
;     ldfrag(st, 1, 1);
;     mma(0);
;     pat_rd();
;     ldfrag(st, 2, 0);
;     mma(1);
;     pat_rd();
;     ldfrag(st, 3, 1);
;     mma(0);
;     pat_rd();
;     asm volatile("s_waitcnt vmcnt(0)" ::: "memory");
;     __syncthreads();
;   }
;   mma(1);
	v_add3_u32 v246, v245, v240, 0
	v_add3_u32 v247, v245, v241, 0
	v_add3_u32 v248, v245, v242, 0
	v_add3_u32 v249, v245, v243, 0
	ds_read_b128 v[190:193], v246 offset:49152
	ds_read_b128 v[194:197], v247 offset:49152
	ds_read_b128 v[198:201], v248 offset:49152
	ds_read_b128 v[228:231], v249 offset:49152
	s_barrier
	s_waitcnt lgkmcnt(0)
	v_mfma_f32_32x32x16_bf16 v[98:113], v[190:193], v[130:133], v[98:113]
	v_mfma_f32_32x32x16_bf16 v[66:81], v[190:193], v[146:149], v[66:81]
	v_mfma_f32_32x32x16_bf16 v[98:113], v[194:197], v[134:137], v[98:113]
	v_mfma_f32_32x32x16_bf16 v[66:81], v[194:197], v[150:153], v[66:81]
	v_mfma_f32_32x32x16_bf16 v[98:113], v[198:201], v[138:141], v[98:113]
	v_mfma_f32_32x32x16_bf16 v[66:81], v[198:201], v[156:159], v[66:81]
	v_mfma_f32_32x32x16_bf16 v[98:113], v[228:231], v[142:145], v[98:113]
	v_mfma_f32_32x32x16_bf16 v[66:81], v[228:231], v[160:163], v[66:81]
	s_barrier
	v_add3_u32 v246, v244, v240, 0
	v_add3_u32 v247, v244, v241, 0
	v_add3_u32 v248, v244, v242, 0
	v_add3_u32 v249, v244, v243, 0
	ds_read_b128 v[130:133], v246 offset:16384
	ds_read_b128 v[134:137], v247 offset:16384
	ds_read_b128 v[138:141], v248 offset:16384
	ds_read_b128 v[142:145], v249 offset:16384
	ds_read_b128 v[146:149], v246 offset:20480
	ds_read_b128 v[150:153], v247 offset:20480
	ds_read_b128 v[156:159], v248 offset:20480
	ds_read_b128 v[160:163], v249 offset:20480
	s_waitcnt vmcnt(4)
	s_barrier
	s_waitcnt lgkmcnt(0)
	v_mfma_f32_32x32x16_bf16 v[50:65], v[170:173], v[130:133], v[50:65]
	v_mfma_f32_32x32x16_bf16 v[18:33], v[170:173], v[146:149], v[18:33]
	v_mfma_f32_32x32x16_bf16 v[50:65], v[174:177], v[134:137], v[50:65]
	v_mfma_f32_32x32x16_bf16 v[18:33], v[174:177], v[150:153], v[18:33]
	v_mfma_f32_32x32x16_bf16 v[50:65], v[178:181], v[138:141], v[50:65]
	v_mfma_f32_32x32x16_bf16 v[18:33], v[178:181], v[156:159], v[18:33]
	v_mfma_f32_32x32x16_bf16 v[50:65], v[186:189], v[142:145], v[50:65]
	v_mfma_f32_32x32x16_bf16 v[18:33], v[186:189], v[160:163], v[18:33]
	v_mfma_f32_32x32x16_bf16 v[34:49], v[190:193], v[130:133], v[34:49]
	v_mfma_f32_32x32x16_bf16 v[2:17], v[190:193], v[146:149], v[2:17]
	v_mfma_f32_32x32x16_bf16 v[34:49], v[194:197], v[134:137], v[34:49]
	v_mfma_f32_32x32x16_bf16 v[2:17], v[194:197], v[150:153], v[2:17]
	v_mfma_f32_32x32x16_bf16 v[34:49], v[198:201], v[138:141], v[34:49]
	v_mfma_f32_32x32x16_bf16 v[2:17], v[198:201], v[156:159], v[2:17]
	v_mfma_f32_32x32x16_bf16 v[34:49], v[228:231], v[142:145], v[34:49]
	v_mfma_f32_32x32x16_bf16 v[2:17], v[228:231], v[160:163], v[2:17]
	s_barrier
	v_add3_u32 v246, v245, v240, s10
	v_add3_u32 v247, v245, v241, s10
	v_add3_u32 v248, v245, v242, s10
	v_add3_u32 v249, v245, v243, s10
	ds_read_b128 v[170:173], v246 offset:32768
	ds_read_b128 v[174:177], v247 offset:32768
	ds_read_b128 v[178:181], v248 offset:32768
	ds_read_b128 v[186:189], v249 offset:32768
	v_add3_u32 v246, v244, v240, s10
	v_add3_u32 v247, v244, v241, s10
	v_add3_u32 v248, v244, v242, s10
	v_add3_u32 v249, v244, v243, s10
	ds_read_b128 v[130:133], v246
	ds_read_b128 v[134:137], v247
	ds_read_b128 v[138:141], v248
	ds_read_b128 v[142:145], v249
	ds_read_b128 v[146:149], v246 offset:4096
	ds_read_b128 v[150:153], v247 offset:4096
	ds_read_b128 v[156:159], v248 offset:4096
	ds_read_b128 v[160:163], v249 offset:4096
	s_waitcnt vmcnt(2)
	s_barrier
	s_waitcnt lgkmcnt(0)
	v_mfma_f32_32x32x16_bf16 v[114:129], v[170:173], v[130:133], v[114:129]
	v_mfma_f32_32x32x16_bf16 v[82:97], v[170:173], v[146:149], v[82:97]
	v_mfma_f32_32x32x16_bf16 v[114:129], v[174:177], v[134:137], v[114:129]
	v_mfma_f32_32x32x16_bf16 v[82:97], v[174:177], v[150:153], v[82:97]
	v_mfma_f32_32x32x16_bf16 v[114:129], v[178:181], v[138:141], v[114:129]
	v_mfma_f32_32x32x16_bf16 v[82:97], v[178:181], v[156:159], v[82:97]
	v_mfma_f32_32x32x16_bf16 v[114:129], v[186:189], v[142:145], v[114:129]
	v_mfma_f32_32x32x16_bf16 v[82:97], v[186:189], v[160:163], v[82:97]
	s_barrier
	v_add3_u32 v246, v245, v240, s10
	v_add3_u32 v247, v245, v241, s10
	v_add3_u32 v248, v245, v242, s10
	v_add3_u32 v249, v245, v243, s10
	ds_read_b128 v[190:193], v246 offset:49152
	ds_read_b128 v[194:197], v247 offset:49152
	ds_read_b128 v[198:201], v248 offset:49152
	ds_read_b128 v[228:231], v249 offset:49152
	s_waitcnt vmcnt(0)
	s_barrier
	s_waitcnt lgkmcnt(0)
	v_mfma_f32_32x32x16_bf16 v[98:113], v[190:193], v[130:133], v[98:113]
	v_mfma_f32_32x32x16_bf16 v[66:81], v[190:193], v[146:149], v[66:81]
	v_mfma_f32_32x32x16_bf16 v[98:113], v[194:197], v[134:137], v[98:113]
	v_mfma_f32_32x32x16_bf16 v[66:81], v[194:197], v[150:153], v[66:81]
	v_mfma_f32_32x32x16_bf16 v[98:113], v[198:201], v[138:141], v[98:113]
	v_mfma_f32_32x32x16_bf16 v[66:81], v[198:201], v[156:159], v[66:81]
	v_mfma_f32_32x32x16_bf16 v[98:113], v[228:231], v[142:145], v[98:113]
	v_mfma_f32_32x32x16_bf16 v[66:81], v[228:231], v[160:163], v[66:81]
	s_barrier
	v_add3_u32 v246, v244, v240, s10
	v_add3_u32 v247, v244, v241, s10
	v_add3_u32 v248, v244, v242, s10
	v_add3_u32 v249, v244, v243, s10
	ds_read_b128 v[130:133], v246 offset:16384
	ds_read_b128 v[134:137], v247 offset:16384
	ds_read_b128 v[138:141], v248 offset:16384
	ds_read_b128 v[142:145], v249 offset:16384
	ds_read_b128 v[146:149], v246 offset:20480
	ds_read_b128 v[150:153], v247 offset:20480
	ds_read_b128 v[156:159], v248 offset:20480
	ds_read_b128 v[160:163], v249 offset:20480
	s_barrier
	s_waitcnt lgkmcnt(0)
	v_mfma_f32_32x32x16_bf16 v[50:65], v[170:173], v[130:133], v[50:65]
	v_mfma_f32_32x32x16_bf16 v[18:33], v[170:173], v[146:149], v[18:33]
	v_mfma_f32_32x32x16_bf16 v[50:65], v[174:177], v[134:137], v[50:65]
	v_mfma_f32_32x32x16_bf16 v[18:33], v[174:177], v[150:153], v[18:33]
	v_mfma_f32_32x32x16_bf16 v[50:65], v[178:181], v[138:141], v[50:65]
	v_mfma_f32_32x32x16_bf16 v[18:33], v[178:181], v[156:159], v[18:33]
	v_mfma_f32_32x32x16_bf16 v[50:65], v[186:189], v[142:145], v[50:65]
	v_mfma_f32_32x32x16_bf16 v[18:33], v[186:189], v[160:163], v[18:33]
	v_mfma_f32_32x32x16_bf16 v[34:49], v[190:193], v[130:133], v[34:49]
	v_mfma_f32_32x32x16_bf16 v[2:17], v[190:193], v[146:149], v[2:17]
	v_mfma_f32_32x32x16_bf16 v[34:49], v[194:197], v[134:137], v[34:49]
	v_mfma_f32_32x32x16_bf16 v[2:17], v[194:197], v[150:153], v[2:17]
	v_mfma_f32_32x32x16_bf16 v[34:49], v[198:201], v[138:141], v[34:49]
	v_mfma_f32_32x32x16_bf16 v[2:17], v[198:201], v[156:159], v[2:17]
	v_mfma_f32_32x32x16_bf16 v[34:49], v[228:231], v[142:145], v[34:49]
	v_mfma_f32_32x32x16_bf16 v[2:17], v[228:231], v[160:163], v[2:17]
	s_barrier
	s_cmp_eq_u32 s101, 0
	s_cbranch_scc0 .Lg8_qb_p1
	s_barrier

; template <bool SWAP>
; DI void gemm_mainloop(f32x16 (&acc)[4][2], const u16* __restrict__ A, int lda, int rlo, int rhi,
;                       const u16* __restrict__ B, int ldb, int K, char* lds, const u16* zero_line) {
;     ...
; #pragma unroll 2
;   for (int kt = 0; kt < nk; ++kt) {
;     const char* st = lds + (kt & 1) * 65536;
;     ldfrag(st, 0, 0);
;     mma(1);
;     pat_rd();
;     if (kt + 1 < nk) glds(kt + 1, (kt + 1) & 1);
;     ldfrag(st, 1, 1);
;     mma(0);
;     pat_rd();
;     ldfrag(st, 2, 0);
;     mma(1);
;     pat_rd();
;     ldfrag(st, 3, 1);
;     mma(0);
;     pat_rd();
;     asm volatile("s_waitcnt vmcnt(0)" ::: "memory");
;     __syncthreads();
;   }
.Lg8_m246_p0:
	s_waitcnt vmcnt(4)
	s_barrier
	s_add_u32 m0, s100, 0x18000
	s_nop 0
	global_load_lds_dwordx4 v232, s[8:9]
	v_add_u32_e32 v232, 0x80, v232
	s_add_u32 m0, s100, 0x1a000
	s_nop 0
	global_load_lds_dwordx4 v234, s[8:9]
	v_add_u32_e32 v234, 0x80, v234
	s_add_u32 m0, s100, 0x10000
	s_nop 0
	global_load_lds_dwordx4 v228, s[6:7]
	v_add_u32_e32 v228, 0x80, v228
	s_add_u32 m0, s100, 0x12000
	s_nop 0
	global_load_lds_dwordx4 v230, s[6:7]
	v_add_u32_e32 v230, 0x80, v230
	s_add_u32 m0, s100, 0x1c000
	s_nop 0
	global_load_lds_dwordx4 v233, s[8:9]
	v_add_u32_e32 v233, 0x80, v233
	s_add_u32 m0, s100, 0x1e000
	s_nop 0
	global_load_lds_dwordx4 v235, s[8:9]
	v_add_u32_e32 v235, 0x80, v235
	s_waitcnt vmcnt(6)
	s_barrier
	v_add3_u32 v242, v241, v236, 0
	v_add3_u32 v243, v241, v237, 0
	v_add3_u32 v244, v241, v238, 0
	v_add3_u32 v245, v241, v239, 0
	ds_read_b128 v[162:165], v242 offset:32768
	ds_read_b128 v[166:169], v243 offset:32768
	ds_read_b128 v[170:173], v244 offset:32768
	ds_read_b128 v[174:177], v245 offset:32768
.Lg8_m246:
	v_add3_u32 v242, v240, v236, 0
	v_add3_u32 v243, v240, v237, 0
	v_add3_u32 v244, v240, v238, 0
	v_add3_u32 v245, v240, v239, 0
	ds_read_b128 v[130:133], v242
	ds_read_b128 v[134:137], v243
	ds_read_b128 v[138:141], v244
	ds_read_b128 v[142:145], v245
	ds_read_b128 v[146:149], v242 offset:4096
	ds_read_b128 v[150:153], v243 offset:4096
	ds_read_b128 v[154:157], v244 offset:4096
	ds_read_b128 v[158:161], v245 offset:4096
	s_add_u32 m0, s100, 0x14000
	s_nop 0
	global_load_lds_dwordx4 v229, s[6:7]
	v_add_u32_e32 v229, 0x80, v229
	s_add_u32 m0, s100, 0x16000
	s_nop 0
	global_load_lds_dwordx4 v231, s[6:7]
	v_add_u32_e32 v231, 0x80, v231
	s_barrier
	s_waitcnt lgkmcnt(0)
	v_mfma_f32_32x32x16_bf16 v[114:129], v[162:165], v[130:133], v[114:129]
	v_mfma_f32_32x32x16_bf16 v[82:97], v[162:165], v[146:149], v[82:97]
	v_mfma_f32_32x32x16_bf16 v[114:129], v[166:169], v[134:137], v[114:129]
	v_mfma_f32_32x32x16_bf16 v[82:97], v[166:169], v[150:153], v[82:97]
	v_mfma_f32_32x32x16_bf16 v[114:129], v[170:173], v[138:141], v[114:129]
	v_mfma_f32_32x32x16_bf16 v[82:97], v[170:173], v[154:157], v[82:97]
	v_mfma_f32_32x32x16_bf16 v[114:129], v[174:177], v[142:145], v[114:129]
	v_mfma_f32_32x32x16_bf16 v[82:97], v[174:177], v[158:161], v[82:97]
	s_barrier
	v_add3_u32 v242, v241, v236, 0
	v_add3_u32 v243, v241, v237, 0
	v_add3_u32 v244, v241, v238, 0
	v_add3_u32 v245, v241, v239, 0
	ds_read_b128 v[180:183], v242 offset:49152
	ds_read_b128 v[186:189], v243 offset:49152
	ds_read_b128 v[190:193], v244 offset:49152
	ds_read_b128 v[194:197], v245 offset:49152
	s_add_u32 m0, s100, 0x8000
	s_nop 0
	global_load_lds_dwordx4 v232, s[8:9]
	v_add_u32_e32 v232, 0x80, v232
	s_add_u32 m0, s100, 0xa000
	s_nop 0
	global_load_lds_dwordx4 v234, s[8:9]
	v_add_u32_e32 v234, 0x80, v234
	s_barrier
	s_waitcnt lgkmcnt(0)
	v_mfma_f32_32x32x16_bf16 v[98:113], v[180:183], v[130:133], v[98:113]
	v_mfma_f32_32x32x16_bf16 v[66:81], v[180:183], v[146:149], v[66:81]
	v_mfma_f32_32x32x16_bf16 v[98:113], v[186:189], v[134:137], v[98:113]
	v_mfma_f32_32x32x16_bf16 v[66:81], v[186:189], v[150:153], v[66:81]
	v_mfma_f32_32x32x16_bf16 v[98:113], v[190:193], v[138:141], v[98:113]
	v_mfma_f32_32x32x16_bf16 v[66:81], v[190:193], v[154:157], v[66:81]
	v_mfma_f32_32x32x16_bf16 v[98:113], v[194:197], v[142:145], v[98:113]
	v_mfma_f32_32x32x16_bf16 v[66:81], v[194:197], v[158:161], v[66:81]
	s_barrier
	v_add3_u32 v242, v240, v236, 0
	v_add3_u32 v243, v240, v237, 0
	v_add3_u32 v244, v240, v238, 0
	v_add3_u32 v245, v240, v239, 0
	ds_read_b128 v[130:133], v242 offset:16384
	ds_read_b128 v[134:137], v243 offset:16384
	ds_read_b128 v[138:141], v244 offset:16384
	ds_read_b128 v[142:145], v245 offset:16384
	ds_read_b128 v[146:149], v242 offset:20480
	ds_read_b128 v[150:153], v243 offset:20480
	ds_read_b128 v[154:157], v244 offset:20480
	ds_read_b128 v[158:161], v245 offset:20480
	s_add_u32 m0, s100, 0x0
	s_nop 0
	global_load_lds_dwordx4 v228, s[6:7]
	v_add_u32_e32 v228, 0x80, v228
	s_add_u32 m0, s100, 0x2000
	s_nop 0
	global_load_lds_dwordx4 v230, s[6:7]
	v_add_u32_e32 v230, 0x80, v230
	s_waitcnt vmcnt(10)
	s_barrier
	s_waitcnt lgkmcnt(0)
	v_mfma_f32_32x32x16_bf16 v[50:65], v[162:165], v[130:133], v[50:65]
	v_mfma_f32_32x32x16_bf16 v[18:33], v[162:165], v[146:149], v[18:33]
	v_mfma_f32_32x32x16_bf16 v[50:65], v[166:169], v[134:137], v[50:65]
	v_mfma_f32_32x32x16_bf16 v[18:33], v[166:169], v[150:153], v[18:33]
	v_mfma_f32_32x32x16_bf16 v[50:65], v[170:173], v[138:141], v[50:65]
	v_mfma_f32_32x32x16_bf16 v[18:33], v[170:173], v[154:157], v[18:33]
	v_mfma_f32_32x32x16_bf16 v[50:65], v[174:177], v[142:145], v[50:65]
	v_mfma_f32_32x32x16_bf16 v[18:33], v[174:177], v[158:161], v[18:33]
	s_barrier
	v_add3_u32 v242, v241, v236, s10
	v_add3_u32 v243, v241, v237, s10
	v_add3_u32 v244, v241, v238, s10
	v_add3_u32 v245, v241, v239, s10
	ds_read_b128 v[162:165], v242 offset:32768
	ds_read_b128 v[166:169], v243 offset:32768
	ds_read_b128 v[170:173], v244 offset:32768
	ds_read_b128 v[174:177], v245 offset:32768
	s_add_u32 m0, s100, 0xc000
	s_nop 0
	global_load_lds_dwordx4 v233, s[8:9]
	v_add_u32_e32 v233, 0x80, v233
	s_add_u32 m0, s100, 0xe000
	s_nop 0
	global_load_lds_dwordx4 v235, s[8:9]
	v_add_u32_e32 v235, 0x80, v235
	s_waitcnt vmcnt(6)
	s_barrier
	s_waitcnt lgkmcnt(0)
	v_mfma_f32_32x32x16_bf16 v[34:49], v[180:183], v[130:133], v[34:49]
	v_mfma_f32_32x32x16_bf16 v[2:17], v[180:183], v[146:149], v[2:17]
	v_mfma_f32_32x32x16_bf16 v[34:49], v[186:189], v[134:137], v[34:49]
	v_mfma_f32_32x32x16_bf16 v[2:17], v[186:189], v[150:153], v[2:17]
	v_mfma_f32_32x32x16_bf16 v[34:49], v[190:193], v[138:141], v[34:49]
	v_mfma_f32_32x32x16_bf16 v[2:17], v[190:193], v[154:157], v[2:17]
	v_mfma_f32_32x32x16_bf16 v[34:49], v[194:197], v[142:145], v[34:49]
	v_mfma_f32_32x32x16_bf16 v[2:17], v[194:197], v[158:161], v[2:17]
	s_barrier
; template <bool SWAP>
; DI void gemm_mainloop(f32x16 (&acc)[4][2], const u16* __restrict__ A, int lda, int rlo, int rhi,
;                       const u16* __restrict__ B, int ldb, int K, char* lds, const u16* zero_line) {
;     ...
; #pragma unroll 2
;   for (int kt = 0; kt < nk; ++kt) {
;     const char* st = lds + (kt & 1) * 65536;
;     ldfrag(st, 0, 0);
;     mma(1);
;     pat_rd();
;     if (kt + 1 < nk) glds(kt + 1, (kt + 1) & 1);
;     ldfrag(st, 1, 1);
;     mma(0);
;     pat_rd();
;     ldfrag(st, 2, 0);
;     mma(1);
;     pat_rd();
;     ldfrag(st, 3, 1);
;     mma(0);
;     pat_rd();
;     asm volatile("s_waitcnt vmcnt(0)" ::: "memory");
;     __syncthreads();
;   }
	v_add3_u32 v242, v240, v236, s10
	v_add3_u32 v243, v240, v237, s10
	v_add3_u32 v244, v240, v238, s10
	v_add3_u32 v245, v240, v239, s10
	ds_read_b128 v[130:133], v242
	ds_read_b128 v[134:137], v243
	ds_read_b128 v[138:141], v244
	ds_read_b128 v[142:145], v245
	ds_read_b128 v[146:149], v242 offset:4096
	ds_read_b128 v[150:153], v243 offset:4096
	ds_read_b128 v[154:157], v244 offset:4096
	ds_read_b128 v[158:161], v245 offset:4096
	s_add_u32 m0, s100, 0x4000
	s_nop 0
	global_load_lds_dwordx4 v229, s[6:7]
	v_add_u32_e32 v229, 0x80, v229
	s_add_u32 m0, s100, 0x6000
	s_nop 0
	global_load_lds_dwordx4 v231, s[6:7]
	v_add_u32_e32 v231, 0x80, v231
	s_barrier
	s_waitcnt lgkmcnt(0)
	v_mfma_f32_32x32x16_bf16 v[114:129], v[162:165], v[130:133], v[114:129]
	v_mfma_f32_32x32x16_bf16 v[82:97], v[162:165], v[146:149], v[82:97]
	v_mfma_f32_32x32x16_bf16 v[114:129], v[166:169], v[134:137], v[114:129]
	v_mfma_f32_32x32x16_bf16 v[82:97], v[166:169], v[150:153], v[82:97]
	v_mfma_f32_32x32x16_bf16 v[114:129], v[170:173], v[138:141], v[114:129]
	v_mfma_f32_32x32x16_bf16 v[82:97], v[170:173], v[154:157], v[82:97]
	v_mfma_f32_32x32x16_bf16 v[114:129], v[174:177], v[142:145], v[114:129]
	v_mfma_f32_32x32x16_bf16 v[82:97], v[174:177], v[158:161], v[82:97]
	s_barrier
	v_add3_u32 v242, v241, v236, s10
	v_add3_u32 v243, v241, v237, s10
	v_add3_u32 v244, v241, v238, s10
	v_add3_u32 v245, v241, v239, s10
	ds_read_b128 v[180:183], v242 offset:49152
	ds_read_b128 v[186:189], v243 offset:49152
	ds_read_b128 v[190:193], v244 offset:49152
	ds_read_b128 v[194:197], v245 offset:49152
	s_add_u32 m0, s100, 0x18000
	s_nop 0
	global_load_lds_dwordx4 v232, s[8:9]
	v_add_u32_e32 v232, 0x80, v232
	s_add_u32 m0, s100, 0x1a000
	s_nop 0
	global_load_lds_dwordx4 v234, s[8:9]
	v_add_u32_e32 v234, 0x80, v234
	s_barrier
	s_waitcnt lgkmcnt(0)
	v_mfma_f32_32x32x16_bf16 v[98:113], v[180:183], v[130:133], v[98:113]
	v_mfma_f32_32x32x16_bf16 v[66:81], v[180:183], v[146:149], v[66:81]
	v_mfma_f32_32x32x16_bf16 v[98:113], v[186:189], v[134:137], v[98:113]
	v_mfma_f32_32x32x16_bf16 v[66:81], v[186:189], v[150:153], v[66:81]
	v_mfma_f32_32x32x16_bf16 v[98:113], v[190:193], v[138:141], v[98:113]
	v_mfma_f32_32x32x16_bf16 v[66:81], v[190:193], v[154:157], v[66:81]
	v_mfma_f32_32x32x16_bf16 v[98:113], v[194:197], v[142:145], v[98:113]
	v_mfma_f32_32x32x16_bf16 v[66:81], v[194:197], v[158:161], v[66:81]
	s_barrier
	v_add3_u32 v242, v240, v236, s10
	v_add3_u32 v243, v240, v237, s10
	v_add3_u32 v244, v240, v238, s10
	v_add3_u32 v245, v240, v239, s10
	ds_read_b128 v[130:133], v242 offset:16384
	ds_read_b128 v[134:137], v243 offset:16384
	ds_read_b128 v[138:141], v244 offset:16384
	ds_read_b128 v[142:145], v245 offset:16384
	ds_read_b128 v[146:149], v242 offset:20480
	ds_read_b128 v[150:153], v243 offset:20480
	ds_read_b128 v[154:157], v244 offset:20480
	ds_read_b128 v[158:161], v245 offset:20480
	s_add_u32 m0, s100, 0x10000
	s_nop 0
	global_load_lds_dwordx4 v228, s[6:7]
	v_add_u32_e32 v228, 0x80, v228
	s_add_u32 m0, s100, 0x12000
	s_nop 0
	global_load_lds_dwordx4 v230, s[6:7]
	v_add_u32_e32 v230, 0x80, v230
	s_waitcnt vmcnt(10)
	s_barrier
	s_waitcnt lgkmcnt(0)
	v_mfma_f32_32x32x16_bf16 v[50:65], v[162:165], v[130:133], v[50:65]
	v_mfma_f32_32x32x16_bf16 v[18:33], v[162:165], v[146:149], v[18:33]
	v_mfma_f32_32x32x16_bf16 v[50:65], v[166:169], v[134:137], v[50:65]
	v_mfma_f32_32x32x16_bf16 v[18:33], v[166:169], v[150:153], v[18:33]
	v_mfma_f32_32x32x16_bf16 v[50:65], v[170:173], v[138:141], v[50:65]
	v_mfma_f32_32x32x16_bf16 v[18:33], v[170:173], v[154:157], v[18:33]
	v_mfma_f32_32x32x16_bf16 v[50:65], v[174:177], v[142:145], v[50:65]
	v_mfma_f32_32x32x16_bf16 v[18:33], v[174:177], v[158:161], v[18:33]
	s_barrier
	v_add3_u32 v242, v241, v236, 0
	v_add3_u32 v243, v241, v237, 0
	v_add3_u32 v244, v241, v238, 0
	v_add3_u32 v245, v241, v239, 0
	ds_read_b128 v[162:165], v242 offset:32768
	ds_read_b128 v[166:169], v243 offset:32768
	ds_read_b128 v[170:173], v244 offset:32768
	ds_read_b128 v[174:177], v245 offset:32768
	s_add_u32 m0, s100, 0x1c000
	s_nop 0
	global_load_lds_dwordx4 v233, s[8:9]
	v_add_u32_e32 v233, 0x80, v233
	s_add_u32 m0, s100, 0x1e000
	s_nop 0
	global_load_lds_dwordx4 v235, s[8:9]
	v_add_u32_e32 v235, 0x80, v235
	s_waitcnt vmcnt(6)
	s_barrier
	s_waitcnt lgkmcnt(0)
	v_mfma_f32_32x32x16_bf16 v[34:49], v[180:183], v[130:133], v[34:49]
	v_mfma_f32_32x32x16_bf16 v[2:17], v[180:183], v[146:149], v[2:17]
	v_mfma_f32_32x32x16_bf16 v[34:49], v[186:189], v[134:137], v[34:49]
	v_mfma_f32_32x32x16_bf16 v[2:17], v[186:189], v[150:153], v[2:17]
	v_mfma_f32_32x32x16_bf16 v[34:49], v[190:193], v[138:141], v[34:49]
	v_mfma_f32_32x32x16_bf16 v[2:17], v[190:193], v[154:157], v[2:17]
	v_mfma_f32_32x32x16_bf16 v[34:49], v[194:197], v[142:145], v[34:49]
	v_mfma_f32_32x32x16_bf16 v[2:17], v[194:197], v[158:161], v[2:17]
	s_barrier
	s_add_i32 s11, s11, 2
	s_cmp_lt_u32 s11, s25
	s_cbranch_scc1 .Lg8_m246
	v_add3_u32 v242, v240, v236, 0
	v_add3_u32 v243, v240, v237, 0
	v_add3_u32 v244, v240, v238, 0
	v_add3_u32 v245, v240, v239, 0
	ds_read_b128 v[130:133], v242
	ds_read_b128 v[134:137], v243
	ds_read_b128 v[138:141], v244
	ds_read_b128 v[142:145], v245
	ds_read_b128 v[146:149], v242 offset:4096
	ds_read_b128 v[150:153], v243 offset:4096
	ds_read_b128 v[154:157], v244 offset:4096
	ds_read_b128 v[158:161], v245 offset:4096
	s_add_u32 m0, s100, 0x14000
	s_nop 0
	global_load_lds_dwordx4 v229, s[6:7]
	v_add_u32_e32 v229, 0x80, v229
	s_add_u32 m0, s100, 0x16000
	s_nop 0
	global_load_lds_dwordx4 v231, s[6:7]
	v_add_u32_e32 v231, 0x80, v231
	s_barrier
; template <bool SWAP>
; DI void gemm_mainloop(f32x16 (&acc)[4][2], const u16* __restrict__ A, int lda, int rlo, int rhi,
;                       const u16* __restrict__ B, int ldb, int K, char* lds, const u16* zero_line) {
;     ...
;   for (int kt = 0; kt < nk; ++kt) {
;     const char* st = lds + (kt & 1) * 65536;
;     ldfrag(st, 0, 0);
;     mma(1);
;     pat_rd();
;     if (kt + 1 < nk) glds(kt + 1, (kt + 1) & 1);
;     ldfrag(st, 1, 1);
;     mma(0);
;     pat_rd();
;     ldfrag(st, 2, 0);
;     mma(1);
;     pat_rd();
;     ldfrag(st, 3, 1);
;     mma(0);
;     pat_rd();
;     asm volatile("s_waitcnt vmcnt(0)" ::: "memory");
;     __syncthreads();
;   }
	s_waitcnt lgkmcnt(0)
	v_mfma_f32_32x32x16_bf16 v[114:129], v[162:165], v[130:133], v[114:129]
	v_mfma_f32_32x32x16_bf16 v[82:97], v[162:165], v[146:149], v[82:97]
	v_mfma_f32_32x32x16_bf16 v[114:129], v[166:169], v[134:137], v[114:129]
	v_mfma_f32_32x32x16_bf16 v[82:97], v[166:169], v[150:153], v[82:97]
	v_mfma_f32_32x32x16_bf16 v[114:129], v[170:173], v[138:141], v[114:129]
	v_mfma_f32_32x32x16_bf16 v[82:97], v[170:173], v[154:157], v[82:97]
	v_mfma_f32_32x32x16_bf16 v[114:129], v[174:177], v[142:145], v[114:129]
	v_mfma_f32_32x32x16_bf16 v[82:97], v[174:177], v[158:161], v[82:97]
	s_barrier
	v_add3_u32 v242, v241, v236, 0
	v_add3_u32 v243, v241, v237, 0
	v_add3_u32 v244, v241, v238, 0
	v_add3_u32 v245, v241, v239, 0
	ds_read_b128 v[180:183], v242 offset:49152
	ds_read_b128 v[186:189], v243 offset:49152
	ds_read_b128 v[190:193], v244 offset:49152
	ds_read_b128 v[194:197], v245 offset:49152
	s_barrier
	s_waitcnt lgkmcnt(0)
	v_mfma_f32_32x32x16_bf16 v[98:113], v[180:183], v[130:133], v[98:113]
	v_mfma_f32_32x32x16_bf16 v[66:81], v[180:183], v[146:149], v[66:81]
	v_mfma_f32_32x32x16_bf16 v[98:113], v[186:189], v[134:137], v[98:113]
	v_mfma_f32_32x32x16_bf16 v[66:81], v[186:189], v[150:153], v[66:81]
	v_mfma_f32_32x32x16_bf16 v[98:113], v[190:193], v[138:141], v[98:113]
	v_mfma_f32_32x32x16_bf16 v[66:81], v[190:193], v[154:157], v[66:81]
	v_mfma_f32_32x32x16_bf16 v[98:113], v[194:197], v[142:145], v[98:113]
	v_mfma_f32_32x32x16_bf16 v[66:81], v[194:197], v[158:161], v[66:81]
	s_barrier
	v_add3_u32 v242, v240, v236, 0
	v_add3_u32 v243, v240, v237, 0
	v_add3_u32 v244, v240, v238, 0
	v_add3_u32 v245, v240, v239, 0
	ds_read_b128 v[130:133], v242 offset:16384
	ds_read_b128 v[134:137], v243 offset:16384
	ds_read_b128 v[138:141], v244 offset:16384
	ds_read_b128 v[142:145], v245 offset:16384
	ds_read_b128 v[146:149], v242 offset:20480
	ds_read_b128 v[150:153], v243 offset:20480
	ds_read_b128 v[154:157], v244 offset:20480
	ds_read_b128 v[158:161], v245 offset:20480
	s_waitcnt vmcnt(4)
	s_barrier
	s_waitcnt lgkmcnt(0)
	v_mfma_f32_32x32x16_bf16 v[50:65], v[162:165], v[130:133], v[50:65]
	v_mfma_f32_32x32x16_bf16 v[18:33], v[162:165], v[146:149], v[18:33]
	v_mfma_f32_32x32x16_bf16 v[50:65], v[166:169], v[134:137], v[50:65]
	v_mfma_f32_32x32x16_bf16 v[18:33], v[166:169], v[150:153], v[18:33]
	v_mfma_f32_32x32x16_bf16 v[50:65], v[170:173], v[138:141], v[50:65]
	v_mfma_f32_32x32x16_bf16 v[18:33], v[170:173], v[154:157], v[18:33]
	v_mfma_f32_32x32x16_bf16 v[50:65], v[174:177], v[142:145], v[50:65]
	v_mfma_f32_32x32x16_bf16 v[18:33], v[174:177], v[158:161], v[18:33]
	v_mfma_f32_32x32x16_bf16 v[34:49], v[180:183], v[130:133], v[34:49]
	v_mfma_f32_32x32x16_bf16 v[2:17], v[180:183], v[146:149], v[2:17]
	v_mfma_f32_32x32x16_bf16 v[34:49], v[186:189], v[134:137], v[34:49]
	v_mfma_f32_32x32x16_bf16 v[2:17], v[186:189], v[150:153], v[2:17]
	v_mfma_f32_32x32x16_bf16 v[34:49], v[190:193], v[138:141], v[34:49]
	v_mfma_f32_32x32x16_bf16 v[2:17], v[190:193], v[154:157], v[2:17]
	v_mfma_f32_32x32x16_bf16 v[34:49], v[194:197], v[142:145], v[34:49]
	v_mfma_f32_32x32x16_bf16 v[2:17], v[194:197], v[158:161], v[2:17]
	s_barrier
	v_add3_u32 v242, v241, v236, s10
	v_add3_u32 v243, v241, v237, s10
	v_add3_u32 v244, v241, v238, s10
	v_add3_u32 v245, v241, v239, s10
	ds_read_b128 v[162:165], v242 offset:32768
	ds_read_b128 v[166:169], v243 offset:32768
	ds_read_b128 v[170:173], v244 offset:32768
	ds_read_b128 v[174:177], v245 offset:32768
	v_add3_u32 v242, v240, v236, s10
	v_add3_u32 v243, v240, v237, s10
	v_add3_u32 v244, v240, v238, s10
	v_add3_u32 v245, v240, v239, s10
	ds_read_b128 v[130:133], v242
	ds_read_b128 v[134:137], v243
	ds_read_b128 v[138:141], v244
	ds_read_b128 v[142:145], v245
	ds_read_b128 v[146:149], v242 offset:4096
	ds_read_b128 v[150:153], v243 offset:4096
	ds_read_b128 v[154:157], v244 offset:4096
	ds_read_b128 v[158:161], v245 offset:4096
	s_waitcnt vmcnt(2)
	s_barrier
; template <bool SWAP>
; DI void gemm_mainloop(f32x16 (&acc)[4][2], const u16* __restrict__ A, int lda, int rlo, int rhi,
;                       const u16* __restrict__ B, int ldb, int K, char* lds, const u16* zero_line) {
;     ...
;   for (int kt = 0; kt < nk; ++kt) {
;     const char* st = lds + (kt & 1) * 65536;
;     ldfrag(st, 0, 0);
;     mma(1);
;     pat_rd();
;     if (kt + 1 < nk) glds(kt + 1, (kt + 1) & 1);
;     ldfrag(st, 1, 1);
;     mma(0);
;     pat_rd();
;     ldfrag(st, 2, 0);
;     mma(1);
;     pat_rd();
;     ldfrag(st, 3, 1);
;     mma(0);
;     pat_rd();
;     asm volatile("s_waitcnt vmcnt(0)" ::: "memory");
;     __syncthreads();
;   }
;   mma(1);
	s_waitcnt lgkmcnt(0)
	v_mfma_f32_32x32x16_bf16 v[114:129], v[162:165], v[130:133], v[114:129]
	v_mfma_f32_32x32x16_bf16 v[82:97], v[162:165], v[146:149], v[82:97]
	v_mfma_f32_32x32x16_bf16 v[114:129], v[166:169], v[134:137], v[114:129]
	v_mfma_f32_32x32x16_bf16 v[82:97], v[166:169], v[150:153], v[82:97]
	v_mfma_f32_32x32x16_bf16 v[114:129], v[170:173], v[138:141], v[114:129]
	v_mfma_f32_32x32x16_bf16 v[82:97], v[170:173], v[154:157], v[82:97]
	v_mfma_f32_32x32x16_bf16 v[114:129], v[174:177], v[142:145], v[114:129]
	v_mfma_f32_32x32x16_bf16 v[82:97], v[174:177], v[158:161], v[82:97]
	s_barrier
	v_add3_u32 v242, v241, v236, s10
	v_add3_u32 v243, v241, v237, s10
	v_add3_u32 v244, v241, v238, s10
	v_add3_u32 v245, v241, v239, s10
	ds_read_b128 v[180:183], v242 offset:49152
	ds_read_b128 v[186:189], v243 offset:49152
	ds_read_b128 v[190:193], v244 offset:49152
	ds_read_b128 v[194:197], v245 offset:49152
	s_waitcnt vmcnt(0)
	s_barrier
	s_waitcnt lgkmcnt(0)
	v_mfma_f32_32x32x16_bf16 v[98:113], v[180:183], v[130:133], v[98:113]
	v_mfma_f32_32x32x16_bf16 v[66:81], v[180:183], v[146:149], v[66:81]
	v_mfma_f32_32x32x16_bf16 v[98:113], v[186:189], v[134:137], v[98:113]
	v_mfma_f32_32x32x16_bf16 v[66:81], v[186:189], v[150:153], v[66:81]
	v_mfma_f32_32x32x16_bf16 v[98:113], v[190:193], v[138:141], v[98:113]
	v_mfma_f32_32x32x16_bf16 v[66:81], v[190:193], v[154:157], v[66:81]
	v_mfma_f32_32x32x16_bf16 v[98:113], v[194:197], v[142:145], v[98:113]
	v_mfma_f32_32x32x16_bf16 v[66:81], v[194:197], v[158:161], v[66:81]
	s_barrier
	v_add3_u32 v242, v240, v236, s10
	v_add3_u32 v243, v240, v237, s10
	v_add3_u32 v244, v240, v238, s10
	v_add3_u32 v245, v240, v239, s10
	ds_read_b128 v[130:133], v242 offset:16384
	ds_read_b128 v[134:137], v243 offset:16384
	ds_read_b128 v[138:141], v244 offset:16384
	ds_read_b128 v[142:145], v245 offset:16384
	ds_read_b128 v[146:149], v242 offset:20480
	ds_read_b128 v[150:153], v243 offset:20480
	ds_read_b128 v[154:157], v244 offset:20480
	ds_read_b128 v[158:161], v245 offset:20480
	s_barrier
	s_waitcnt lgkmcnt(0)
	v_mfma_f32_32x32x16_bf16 v[50:65], v[162:165], v[130:133], v[50:65]
	v_mfma_f32_32x32x16_bf16 v[18:33], v[162:165], v[146:149], v[18:33]
	v_mfma_f32_32x32x16_bf16 v[50:65], v[166:169], v[134:137], v[50:65]
	v_mfma_f32_32x32x16_bf16 v[18:33], v[166:169], v[150:153], v[18:33]
	v_mfma_f32_32x32x16_bf16 v[50:65], v[170:173], v[138:141], v[50:65]
	v_mfma_f32_32x32x16_bf16 v[18:33], v[170:173], v[154:157], v[18:33]
	v_mfma_f32_32x32x16_bf16 v[50:65], v[174:177], v[142:145], v[50:65]
	v_mfma_f32_32x32x16_bf16 v[18:33], v[174:177], v[158:161], v[18:33]
	v_mfma_f32_32x32x16_bf16 v[34:49], v[180:183], v[130:133], v[34:49]
	v_mfma_f32_32x32x16_bf16 v[2:17], v[180:183], v[146:149], v[2:17]
	v_mfma_f32_32x32x16_bf16 v[34:49], v[186:189], v[134:137], v[34:49]
	v_mfma_f32_32x32x16_bf16 v[2:17], v[186:189], v[150:153], v[2:17]
	v_mfma_f32_32x32x16_bf16 v[34:49], v[190:193], v[138:141], v[34:49]
	v_mfma_f32_32x32x16_bf16 v[2:17], v[190:193], v[154:157], v[2:17]
	v_mfma_f32_32x32x16_bf16 v[34:49], v[194:197], v[142:145], v[34:49]
	v_mfma_f32_32x32x16_bf16 v[2:17], v[194:197], v[158:161], v[2:17]
	s_barrier
	s_cmp_eq_u32 s101, 0
	s_cbranch_scc0 .Lg8_m246_p1
	s_barrier

; template <bool SWAP>
; DI void gemm_mainloop(f32x16 (&acc)[4][2], const u16* __restrict__ A, int lda, int rlo, int rhi,
;                       const u16* __restrict__ B, int ldb, int K, char* lds, const u16* zero_line) {
;     ...
; #pragma unroll 2
;   for (int kt = 0; kt < nk; ++kt) {
;     const char* st = lds + (kt & 1) * 65536;
;     ldfrag(st, 0, 0);
;     mma(1);
;     pat_rd();
;     if (kt + 1 < nk) glds(kt + 1, (kt + 1) & 1);
;     ldfrag(st, 1, 1);
;     mma(0);
;     pat_rd();
;     ldfrag(st, 2, 0);
;     mma(1);
;     pat_rd();
;     ldfrag(st, 3, 1);
;     mma(0);
;     pat_rd();
;     asm volatile("s_waitcnt vmcnt(0)" ::: "memory");
;     __syncthreads();
;   }
.Lg8_ia_p0:
	s_waitcnt vmcnt(4)
	s_barrier
	s_add_u32 m0, s100, 0x18000
	s_nop 0
	global_load_lds_dwordx4 v244, s[8:9]
	v_add_u32_e32 v244, 0x80, v244
	s_add_u32 m0, s100, 0x1a000
	s_nop 0
	global_load_lds_dwordx4 v246, s[8:9]
	v_add_u32_e32 v246, 0x80, v246
	s_add_u32 m0, s100, 0x10000
	s_nop 0
	global_load_lds_dwordx4 v240, s[6:7]
	v_add_u32_e32 v240, 0x80, v240
	s_add_u32 m0, s100, 0x12000
	s_nop 0
	global_load_lds_dwordx4 v242, s[6:7]
	v_add_u32_e32 v242, 0x80, v242
	s_add_u32 m0, s100, 0x1c000
	s_nop 0
	global_load_lds_dwordx4 v245, s[8:9]
	v_add_u32_e32 v245, 0x80, v245
	s_add_u32 m0, s100, 0x1e000
	s_nop 0
	global_load_lds_dwordx4 v247, s[8:9]
	v_add_u32_e32 v247, 0x80, v247
	s_waitcnt vmcnt(6)
	s_barrier
	v_add3_u32 v187, v186, v161, 0
	v_add3_u32 v248, v186, v163, 0
	ds_read_b128 v[176:179], v187 offset:32768
	ds_read_b128 v[180:183], v248 offset:32768
	v_add3_u32 v187, v186, v164, 0
	v_add3_u32 v248, v186, v165, 0
	ds_read_b128 v[192:195], v187 offset:32768
	ds_read_b128 v[196:199], v248 offset:32768
.Lg8_ia:
	v_add3_u32 v187, v166, v161, 0
	v_add3_u32 v248, v166, v163, 0
	ds_read_b128 v[130:133], v187
	ds_read_b128 v[134:137], v248
	ds_read_b128 v[146:149], v187 offset:4096
	ds_read_b128 v[150:153], v248 offset:4096
	v_add3_u32 v187, v166, v164, 0
	v_add3_u32 v248, v166, v165, 0
	ds_read_b128 v[138:141], v187
	ds_read_b128 v[142:145], v248
	ds_read_b128 v[168:171], v187 offset:4096
	ds_read_b128 v[172:175], v248 offset:4096
	s_add_u32 m0, s100, 0x14000
	s_nop 0
	global_load_lds_dwordx4 v241, s[6:7]
	v_add_u32_e32 v241, 0x80, v241
	s_add_u32 m0, s100, 0x16000
	s_nop 0
	global_load_lds_dwordx4 v243, s[6:7]
	v_add_u32_e32 v243, 0x80, v243
	s_barrier
	s_waitcnt lgkmcnt(0)
	v_mfma_f32_32x32x16_bf16 v[114:129], v[176:179], v[130:133], v[114:129]
	v_mfma_f32_32x32x16_bf16 v[98:113], v[176:179], v[146:149], v[98:113]
	v_mfma_f32_32x32x16_bf16 v[114:129], v[180:183], v[134:137], v[114:129]
	v_mfma_f32_32x32x16_bf16 v[98:113], v[180:183], v[150:153], v[98:113]
	v_mfma_f32_32x32x16_bf16 v[114:129], v[192:195], v[138:141], v[114:129]
	v_mfma_f32_32x32x16_bf16 v[98:113], v[192:195], v[168:171], v[98:113]
	v_mfma_f32_32x32x16_bf16 v[114:129], v[196:199], v[142:145], v[114:129]
	v_mfma_f32_32x32x16_bf16 v[98:113], v[196:199], v[172:175], v[98:113]
	s_barrier
	v_add3_u32 v187, v186, v161, 0
	v_add3_u32 v248, v186, v163, 0
	ds_read_b128 v[200:203], v187 offset:49152
	ds_read_b128 v[228:231], v248 offset:49152
	v_add3_u32 v187, v186, v164, 0
	v_add3_u32 v248, v186, v165, 0
	ds_read_b128 v[232:235], v187 offset:49152
	ds_read_b128 v[236:239], v248 offset:49152
	s_add_u32 m0, s100, 0x8000
	s_nop 0
	global_load_lds_dwordx4 v244, s[8:9]
	v_add_u32_e32 v244, 0x80, v244
	s_add_u32 m0, s100, 0xa000
	s_nop 0
	global_load_lds_dwordx4 v246, s[8:9]
	v_add_u32_e32 v246, 0x80, v246
	s_barrier
	s_waitcnt lgkmcnt(0)
	v_mfma_f32_32x32x16_bf16 v[82:97], v[200:203], v[130:133], v[82:97]
	v_mfma_f32_32x32x16_bf16 v[50:65], v[200:203], v[146:149], v[50:65]
	v_mfma_f32_32x32x16_bf16 v[82:97], v[228:231], v[134:137], v[82:97]
	v_mfma_f32_32x32x16_bf16 v[50:65], v[228:231], v[150:153], v[50:65]
	v_mfma_f32_32x32x16_bf16 v[82:97], v[232:235], v[138:141], v[82:97]
	v_mfma_f32_32x32x16_bf16 v[50:65], v[232:235], v[168:171], v[50:65]
	v_mfma_f32_32x32x16_bf16 v[82:97], v[236:239], v[142:145], v[82:97]
	v_mfma_f32_32x32x16_bf16 v[50:65], v[236:239], v[172:175], v[50:65]
	s_barrier
	v_add3_u32 v187, v166, v161, 0
	v_add3_u32 v248, v166, v163, 0
	ds_read_b128 v[130:133], v187 offset:16384
	ds_read_b128 v[134:137], v248 offset:16384
	ds_read_b128 v[146:149], v187 offset:20480
	ds_read_b128 v[150:153], v248 offset:20480
	v_add3_u32 v187, v166, v164, 0
	v_add3_u32 v248, v166, v165, 0
	ds_read_b128 v[138:141], v187 offset:16384
	ds_read_b128 v[142:145], v248 offset:16384
	ds_read_b128 v[168:171], v187 offset:20480
	ds_read_b128 v[172:175], v248 offset:20480
	s_add_u32 m0, s100, 0x0
	s_nop 0
	global_load_lds_dwordx4 v240, s[6:7]
	v_add_u32_e32 v240, 0x80, v240
	s_add_u32 m0, s100, 0x2000
	s_nop 0
	global_load_lds_dwordx4 v242, s[6:7]
	v_add_u32_e32 v242, 0x80, v242
	s_waitcnt vmcnt(10)
	s_barrier
	s_waitcnt lgkmcnt(0)
	v_mfma_f32_32x32x16_bf16 v[66:81], v[176:179], v[130:133], v[66:81]
	v_mfma_f32_32x32x16_bf16 v[34:49], v[176:179], v[146:149], v[34:49]
	v_mfma_f32_32x32x16_bf16 v[66:81], v[180:183], v[134:137], v[66:81]
	v_mfma_f32_32x32x16_bf16 v[34:49], v[180:183], v[150:153], v[34:49]
	v_mfma_f32_32x32x16_bf16 v[66:81], v[192:195], v[138:141], v[66:81]
	v_mfma_f32_32x32x16_bf16 v[34:49], v[192:195], v[168:171], v[34:49]
	v_mfma_f32_32x32x16_bf16 v[66:81], v[196:199], v[142:145], v[66:81]
	v_mfma_f32_32x32x16_bf16 v[34:49], v[196:199], v[172:175], v[34:49]
	s_barrier
	v_add3_u32 v187, v186, v161, s10
	v_add3_u32 v248, v186, v163, s10
	ds_read_b128 v[176:179], v187 offset:32768
	ds_read_b128 v[180:183], v248 offset:32768
	v_add3_u32 v187, v186, v164, s10
	v_add3_u32 v248, v186, v165, s10
	ds_read_b128 v[192:195], v187 offset:32768
	ds_read_b128 v[196:199], v248 offset:32768
	s_add_u32 m0, s100, 0xc000
	s_nop 0
	global_load_lds_dwordx4 v245, s[8:9]
	v_add_u32_e32 v245, 0x80, v245
	s_add_u32 m0, s100, 0xe000
	s_nop 0
	global_load_lds_dwordx4 v247, s[8:9]
	v_add_u32_e32 v247, 0x80, v247
	s_waitcnt vmcnt(6)
	s_barrier
	s_waitcnt lgkmcnt(0)
	v_mfma_f32_32x32x16_bf16 v[18:33], v[200:203], v[130:133], v[18:33]
	v_mfma_f32_32x32x16_bf16 v[2:17], v[200:203], v[146:149], v[2:17]
	v_mfma_f32_32x32x16_bf16 v[18:33], v[228:231], v[134:137], v[18:33]
	v_mfma_f32_32x32x16_bf16 v[2:17], v[228:231], v[150:153], v[2:17]
	v_mfma_f32_32x32x16_bf16 v[18:33], v[232:235], v[138:141], v[18:33]
	v_mfma_f32_32x32x16_bf16 v[2:17], v[232:235], v[168:171], v[2:17]
	v_mfma_f32_32x32x16_bf16 v[18:33], v[236:239], v[142:145], v[18:33]
	v_mfma_f32_32x32x16_bf16 v[2:17], v[236:239], v[172:175], v[2:17]
	s_barrier
; template <bool SWAP>
; DI void gemm_mainloop(f32x16 (&acc)[4][2], const u16* __restrict__ A, int lda, int rlo, int rhi,
;                       const u16* __restrict__ B, int ldb, int K, char* lds, const u16* zero_line) {
;     ...
; #pragma unroll 2
;   for (int kt = 0; kt < nk; ++kt) {
;     const char* st = lds + (kt & 1) * 65536;
;     ldfrag(st, 0, 0);
;     mma(1);
;     pat_rd();
;     if (kt + 1 < nk) glds(kt + 1, (kt + 1) & 1);
;     ldfrag(st, 1, 1);
;     mma(0);
;     pat_rd();
;     ldfrag(st, 2, 0);
;     mma(1);
;     pat_rd();
;     ldfrag(st, 3, 1);
;     mma(0);
;     pat_rd();
;     asm volatile("s_waitcnt vmcnt(0)" ::: "memory");
;     __syncthreads();
;   }
	v_add3_u32 v187, v166, v161, s10
	v_add3_u32 v248, v166, v163, s10
	ds_read_b128 v[130:133], v187
	ds_read_b128 v[134:137], v248
	ds_read_b128 v[146:149], v187 offset:4096
	ds_read_b128 v[150:153], v248 offset:4096
	v_add3_u32 v187, v166, v164, s10
	v_add3_u32 v248, v166, v165, s10
	ds_read_b128 v[138:141], v187
	ds_read_b128 v[142:145], v248
	ds_read_b128 v[168:171], v187 offset:4096
	ds_read_b128 v[172:175], v248 offset:4096
	s_add_u32 m0, s100, 0x4000
	s_nop 0
	global_load_lds_dwordx4 v241, s[6:7]
	v_add_u32_e32 v241, 0x80, v241
	s_add_u32 m0, s100, 0x6000
	s_nop 0
	global_load_lds_dwordx4 v243, s[6:7]
	v_add_u32_e32 v243, 0x80, v243
	s_barrier
	s_waitcnt lgkmcnt(0)
	v_mfma_f32_32x32x16_bf16 v[114:129], v[176:179], v[130:133], v[114:129]
	v_mfma_f32_32x32x16_bf16 v[98:113], v[176:179], v[146:149], v[98:113]
	v_mfma_f32_32x32x16_bf16 v[114:129], v[180:183], v[134:137], v[114:129]
	v_mfma_f32_32x32x16_bf16 v[98:113], v[180:183], v[150:153], v[98:113]
	v_mfma_f32_32x32x16_bf16 v[114:129], v[192:195], v[138:141], v[114:129]
	v_mfma_f32_32x32x16_bf16 v[98:113], v[192:195], v[168:171], v[98:113]
	v_mfma_f32_32x32x16_bf16 v[114:129], v[196:199], v[142:145], v[114:129]
	v_mfma_f32_32x32x16_bf16 v[98:113], v[196:199], v[172:175], v[98:113]
	s_barrier
	v_add3_u32 v187, v186, v161, s10
	v_add3_u32 v248, v186, v163, s10
	ds_read_b128 v[200:203], v187 offset:49152
	ds_read_b128 v[228:231], v248 offset:49152
	v_add3_u32 v187, v186, v164, s10
	v_add3_u32 v248, v186, v165, s10
	ds_read_b128 v[232:235], v187 offset:49152
	ds_read_b128 v[236:239], v248 offset:49152
	s_add_u32 m0, s100, 0x18000
	s_nop 0
	global_load_lds_dwordx4 v244, s[8:9]
	v_add_u32_e32 v244, 0x80, v244
	s_add_u32 m0, s100, 0x1a000
	s_nop 0
	global_load_lds_dwordx4 v246, s[8:9]
	v_add_u32_e32 v246, 0x80, v246
	s_barrier
	s_waitcnt lgkmcnt(0)
	v_mfma_f32_32x32x16_bf16 v[82:97], v[200:203], v[130:133], v[82:97]
	v_mfma_f32_32x32x16_bf16 v[50:65], v[200:203], v[146:149], v[50:65]
	v_mfma_f32_32x32x16_bf16 v[82:97], v[228:231], v[134:137], v[82:97]
	v_mfma_f32_32x32x16_bf16 v[50:65], v[228:231], v[150:153], v[50:65]
	v_mfma_f32_32x32x16_bf16 v[82:97], v[232:235], v[138:141], v[82:97]
	v_mfma_f32_32x32x16_bf16 v[50:65], v[232:235], v[168:171], v[50:65]
	v_mfma_f32_32x32x16_bf16 v[82:97], v[236:239], v[142:145], v[82:97]
	v_mfma_f32_32x32x16_bf16 v[50:65], v[236:239], v[172:175], v[50:65]
	s_barrier
	v_add3_u32 v187, v166, v161, s10
	v_add3_u32 v248, v166, v163, s10
	ds_read_b128 v[130:133], v187 offset:16384
	ds_read_b128 v[134:137], v248 offset:16384
	ds_read_b128 v[146:149], v187 offset:20480
	ds_read_b128 v[150:153], v248 offset:20480
	v_add3_u32 v187, v166, v164, s10
	v_add3_u32 v248, v166, v165, s10
	ds_read_b128 v[138:141], v187 offset:16384
	ds_read_b128 v[142:145], v248 offset:16384
	ds_read_b128 v[168:171], v187 offset:20480
	ds_read_b128 v[172:175], v248 offset:20480
	s_add_u32 m0, s100, 0x10000
	s_nop 0
	global_load_lds_dwordx4 v240, s[6:7]
	v_add_u32_e32 v240, 0x80, v240
	s_add_u32 m0, s100, 0x12000
	s_nop 0
	global_load_lds_dwordx4 v242, s[6:7]
	v_add_u32_e32 v242, 0x80, v242
	s_waitcnt vmcnt(10)
	s_barrier
	s_waitcnt lgkmcnt(0)
	v_mfma_f32_32x32x16_bf16 v[66:81], v[176:179], v[130:133], v[66:81]
	v_mfma_f32_32x32x16_bf16 v[34:49], v[176:179], v[146:149], v[34:49]
	v_mfma_f32_32x32x16_bf16 v[66:81], v[180:183], v[134:137], v[66:81]
	v_mfma_f32_32x32x16_bf16 v[34:49], v[180:183], v[150:153], v[34:49]
	v_mfma_f32_32x32x16_bf16 v[66:81], v[192:195], v[138:141], v[66:81]
	v_mfma_f32_32x32x16_bf16 v[34:49], v[192:195], v[168:171], v[34:49]
	v_mfma_f32_32x32x16_bf16 v[66:81], v[196:199], v[142:145], v[66:81]
	v_mfma_f32_32x32x16_bf16 v[34:49], v[196:199], v[172:175], v[34:49]
	s_barrier
	v_add3_u32 v187, v186, v161, 0
	v_add3_u32 v248, v186, v163, 0
	ds_read_b128 v[176:179], v187 offset:32768
	ds_read_b128 v[180:183], v248 offset:32768
	v_add3_u32 v187, v186, v164, 0
	v_add3_u32 v248, v186, v165, 0
	ds_read_b128 v[192:195], v187 offset:32768
	ds_read_b128 v[196:199], v248 offset:32768
	s_add_u32 m0, s100, 0x1c000
	s_nop 0
	global_load_lds_dwordx4 v245, s[8:9]
	v_add_u32_e32 v245, 0x80, v245
	s_add_u32 m0, s100, 0x1e000
	s_nop 0
	global_load_lds_dwordx4 v247, s[8:9]
	v_add_u32_e32 v247, 0x80, v247
	s_waitcnt vmcnt(6)
	s_barrier
	s_waitcnt lgkmcnt(0)
	v_mfma_f32_32x32x16_bf16 v[18:33], v[200:203], v[130:133], v[18:33]
	v_mfma_f32_32x32x16_bf16 v[2:17], v[200:203], v[146:149], v[2:17]
	v_mfma_f32_32x32x16_bf16 v[18:33], v[228:231], v[134:137], v[18:33]
	v_mfma_f32_32x32x16_bf16 v[2:17], v[228:231], v[150:153], v[2:17]
	v_mfma_f32_32x32x16_bf16 v[18:33], v[232:235], v[138:141], v[18:33]
	v_mfma_f32_32x32x16_bf16 v[2:17], v[232:235], v[168:171], v[2:17]
	v_mfma_f32_32x32x16_bf16 v[18:33], v[236:239], v[142:145], v[18:33]
	v_mfma_f32_32x32x16_bf16 v[2:17], v[236:239], v[172:175], v[2:17]
	s_barrier
	s_add_i32 s11, s11, 2
	s_cmp_lt_u32 s11, 14
	s_cbranch_scc1 .Lg8_ia
	v_add3_u32 v187, v166, v161, 0
	v_add3_u32 v248, v166, v163, 0
	ds_read_b128 v[130:133], v187
	ds_read_b128 v[134:137], v248
	ds_read_b128 v[146:149], v187 offset:4096
	ds_read_b128 v[150:153], v248 offset:4096
	v_add3_u32 v187, v166, v164, 0
	v_add3_u32 v248, v166, v165, 0
	ds_read_b128 v[138:141], v187
	ds_read_b128 v[142:145], v248
	ds_read_b128 v[168:171], v187 offset:4096
	ds_read_b128 v[172:175], v248 offset:4096
	s_add_u32 m0, s100, 0x14000
	s_nop 0
	global_load_lds_dwordx4 v241, s[6:7]
	v_add_u32_e32 v241, 0x80, v241
	s_add_u32 m0, s100, 0x16000
	s_nop 0
	global_load_lds_dwordx4 v243, s[6:7]
	v_add_u32_e32 v243, 0x80, v243
	s_barrier
; template <bool SWAP>
; DI void gemm_mainloop(f32x16 (&acc)[4][2], const u16* __restrict__ A, int lda, int rlo, int rhi,
;                       const u16* __restrict__ B, int ldb, int K, char* lds, const u16* zero_line) {
;     ...
;   for (int kt = 0; kt < nk; ++kt) {
;     const char* st = lds + (kt & 1) * 65536;
;     ldfrag(st, 0, 0);
;     mma(1);
;     pat_rd();
;     if (kt + 1 < nk) glds(kt + 1, (kt + 1) & 1);
;     ldfrag(st, 1, 1);
;     mma(0);
;     pat_rd();
;     ldfrag(st, 2, 0);
;     mma(1);
;     pat_rd();
;     ldfrag(st, 3, 1);
;     mma(0);
;     pat_rd();
;     asm volatile("s_waitcnt vmcnt(0)" ::: "memory");
;     __syncthreads();
;   }
	s_waitcnt lgkmcnt(0)
	v_mfma_f32_32x32x16_bf16 v[114:129], v[176:179], v[130:133], v[114:129]
	v_mfma_f32_32x32x16_bf16 v[98:113], v[176:179], v[146:149], v[98:113]
	v_mfma_f32_32x32x16_bf16 v[114:129], v[180:183], v[134:137], v[114:129]
	v_mfma_f32_32x32x16_bf16 v[98:113], v[180:183], v[150:153], v[98:113]
	v_mfma_f32_32x32x16_bf16 v[114:129], v[192:195], v[138:141], v[114:129]
	v_mfma_f32_32x32x16_bf16 v[98:113], v[192:195], v[168:171], v[98:113]
	v_mfma_f32_32x32x16_bf16 v[114:129], v[196:199], v[142:145], v[114:129]
	v_mfma_f32_32x32x16_bf16 v[98:113], v[196:199], v[172:175], v[98:113]
	s_barrier
	v_add3_u32 v187, v186, v161, 0
	v_add3_u32 v248, v186, v163, 0
	ds_read_b128 v[200:203], v187 offset:49152
	ds_read_b128 v[228:231], v248 offset:49152
	v_add3_u32 v187, v186, v164, 0
	v_add3_u32 v248, v186, v165, 0
	ds_read_b128 v[232:235], v187 offset:49152
	ds_read_b128 v[236:239], v248 offset:49152
	s_barrier
	s_waitcnt lgkmcnt(0)
	v_mfma_f32_32x32x16_bf16 v[82:97], v[200:203], v[130:133], v[82:97]
	v_mfma_f32_32x32x16_bf16 v[50:65], v[200:203], v[146:149], v[50:65]
	v_mfma_f32_32x32x16_bf16 v[82:97], v[228:231], v[134:137], v[82:97]
	v_mfma_f32_32x32x16_bf16 v[50:65], v[228:231], v[150:153], v[50:65]
	v_mfma_f32_32x32x16_bf16 v[82:97], v[232:235], v[138:141], v[82:97]
	v_mfma_f32_32x32x16_bf16 v[50:65], v[232:235], v[168:171], v[50:65]
	v_mfma_f32_32x32x16_bf16 v[82:97], v[236:239], v[142:145], v[82:97]
	v_mfma_f32_32x32x16_bf16 v[50:65], v[236:239], v[172:175], v[50:65]
	s_barrier
	v_add3_u32 v187, v166, v161, 0
	v_add3_u32 v248, v166, v163, 0
	ds_read_b128 v[130:133], v187 offset:16384
	ds_read_b128 v[134:137], v248 offset:16384
	ds_read_b128 v[146:149], v187 offset:20480
	ds_read_b128 v[150:153], v248 offset:20480
	v_add3_u32 v187, v166, v164, 0
	v_add3_u32 v248, v166, v165, 0
	ds_read_b128 v[138:141], v187 offset:16384
	ds_read_b128 v[142:145], v248 offset:16384
	ds_read_b128 v[168:171], v187 offset:20480
	ds_read_b128 v[172:175], v248 offset:20480
	s_waitcnt vmcnt(4)
	s_barrier
	s_waitcnt lgkmcnt(0)
	v_mfma_f32_32x32x16_bf16 v[66:81], v[176:179], v[130:133], v[66:81]
	v_mfma_f32_32x32x16_bf16 v[34:49], v[176:179], v[146:149], v[34:49]
	v_mfma_f32_32x32x16_bf16 v[66:81], v[180:183], v[134:137], v[66:81]
	v_mfma_f32_32x32x16_bf16 v[34:49], v[180:183], v[150:153], v[34:49]
	v_mfma_f32_32x32x16_bf16 v[66:81], v[192:195], v[138:141], v[66:81]
	v_mfma_f32_32x32x16_bf16 v[34:49], v[192:195], v[168:171], v[34:49]
	v_mfma_f32_32x32x16_bf16 v[66:81], v[196:199], v[142:145], v[66:81]
	v_mfma_f32_32x32x16_bf16 v[34:49], v[196:199], v[172:175], v[34:49]
	v_mfma_f32_32x32x16_bf16 v[18:33], v[200:203], v[130:133], v[18:33]
	v_mfma_f32_32x32x16_bf16 v[2:17], v[200:203], v[146:149], v[2:17]
	v_mfma_f32_32x32x16_bf16 v[18:33], v[228:231], v[134:137], v[18:33]
	v_mfma_f32_32x32x16_bf16 v[2:17], v[228:231], v[150:153], v[2:17]
	v_mfma_f32_32x32x16_bf16 v[18:33], v[232:235], v[138:141], v[18:33]
	v_mfma_f32_32x32x16_bf16 v[2:17], v[232:235], v[168:171], v[2:17]
	v_mfma_f32_32x32x16_bf16 v[18:33], v[236:239], v[142:145], v[18:33]
	v_mfma_f32_32x32x16_bf16 v[2:17], v[236:239], v[172:175], v[2:17]
	s_barrier
	v_add3_u32 v187, v186, v161, s10
	v_add3_u32 v248, v186, v163, s10
	ds_read_b128 v[176:179], v187 offset:32768
	ds_read_b128 v[180:183], v248 offset:32768
	v_add3_u32 v187, v186, v164, s10
	v_add3_u32 v248, v186, v165, s10
	ds_read_b128 v[192:195], v187 offset:32768
	ds_read_b128 v[196:199], v248 offset:32768
	v_add3_u32 v187, v166, v161, s10
	v_add3_u32 v248, v166, v163, s10
	ds_read_b128 v[130:133], v187
	ds_read_b128 v[134:137], v248
	ds_read_b128 v[146:149], v187 offset:4096
	ds_read_b128 v[150:153], v248 offset:4096
	v_add3_u32 v187, v166, v164, s10
	v_add3_u32 v248, v166, v165, s10
	ds_read_b128 v[138:141], v187
	ds_read_b128 v[142:145], v248
	ds_read_b128 v[168:171], v187 offset:4096
	ds_read_b128 v[172:175], v248 offset:4096
	s_waitcnt vmcnt(2)
	s_barrier
; template <bool SWAP>
; DI void gemm_mainloop(f32x16 (&acc)[4][2], const u16* __restrict__ A, int lda, int rlo, int rhi,
;                       const u16* __restrict__ B, int ldb, int K, char* lds, const u16* zero_line) {
;     ...
;   for (int kt = 0; kt < nk; ++kt) {
;     const char* st = lds + (kt & 1) * 65536;
;     ldfrag(st, 0, 0);
;     mma(1);
;     pat_rd();
;     if (kt + 1 < nk) glds(kt + 1, (kt + 1) & 1);
;     ldfrag(st, 1, 1);
;     mma(0);
;     pat_rd();
;     ldfrag(st, 2, 0);
;     mma(1);
;     pat_rd();
;     ldfrag(st, 3, 1);
;     mma(0);
;     pat_rd();
;     asm volatile("s_waitcnt vmcnt(0)" ::: "memory");
;     __syncthreads();
;   }
;   mma(1);
	s_waitcnt lgkmcnt(0)
	v_mfma_f32_32x32x16_bf16 v[114:129], v[176:179], v[130:133], v[114:129]
	v_mfma_f32_32x32x16_bf16 v[98:113], v[176:179], v[146:149], v[98:113]
	v_mfma_f32_32x32x16_bf16 v[114:129], v[180:183], v[134:137], v[114:129]
	v_mfma_f32_32x32x16_bf16 v[98:113], v[180:183], v[150:153], v[98:113]
	v_mfma_f32_32x32x16_bf16 v[114:129], v[192:195], v[138:141], v[114:129]
	v_mfma_f32_32x32x16_bf16 v[98:113], v[192:195], v[168:171], v[98:113]
	v_mfma_f32_32x32x16_bf16 v[114:129], v[196:199], v[142:145], v[114:129]
	v_mfma_f32_32x32x16_bf16 v[98:113], v[196:199], v[172:175], v[98:113]
	s_barrier
	v_add3_u32 v187, v186, v161, s10
	v_add3_u32 v248, v186, v163, s10
	ds_read_b128 v[200:203], v187 offset:49152
	ds_read_b128 v[228:231], v248 offset:49152
	v_add3_u32 v187, v186, v164, s10
	v_add3_u32 v248, v186, v165, s10
	ds_read_b128 v[232:235], v187 offset:49152
	ds_read_b128 v[236:239], v248 offset:49152
	s_waitcnt vmcnt(0)
	s_barrier
	s_waitcnt lgkmcnt(0)
	v_mfma_f32_32x32x16_bf16 v[82:97], v[200:203], v[130:133], v[82:97]
	v_mfma_f32_32x32x16_bf16 v[50:65], v[200:203], v[146:149], v[50:65]
	v_mfma_f32_32x32x16_bf16 v[82:97], v[228:231], v[134:137], v[82:97]
	v_mfma_f32_32x32x16_bf16 v[50:65], v[228:231], v[150:153], v[50:65]
	v_mfma_f32_32x32x16_bf16 v[82:97], v[232:235], v[138:141], v[82:97]
	v_mfma_f32_32x32x16_bf16 v[50:65], v[232:235], v[168:171], v[50:65]
	v_mfma_f32_32x32x16_bf16 v[82:97], v[236:239], v[142:145], v[82:97]
	v_mfma_f32_32x32x16_bf16 v[50:65], v[236:239], v[172:175], v[50:65]
	s_barrier
	v_add3_u32 v187, v166, v161, s10
	v_add3_u32 v248, v166, v163, s10
	ds_read_b128 v[130:133], v187 offset:16384
	ds_read_b128 v[134:137], v248 offset:16384
	ds_read_b128 v[146:149], v187 offset:20480
	ds_read_b128 v[150:153], v248 offset:20480
	v_add3_u32 v187, v166, v164, s10
	v_add3_u32 v248, v166, v165, s10
	ds_read_b128 v[138:141], v187 offset:16384
	ds_read_b128 v[142:145], v248 offset:16384
	ds_read_b128 v[168:171], v187 offset:20480
	ds_read_b128 v[172:175], v248 offset:20480
	s_barrier
	s_waitcnt lgkmcnt(0)
	v_mfma_f32_32x32x16_bf16 v[66:81], v[176:179], v[130:133], v[66:81]
	v_mfma_f32_32x32x16_bf16 v[34:49], v[176:179], v[146:149], v[34:49]
	v_mfma_f32_32x32x16_bf16 v[66:81], v[180:183], v[134:137], v[66:81]
	v_mfma_f32_32x32x16_bf16 v[34:49], v[180:183], v[150:153], v[34:49]
	v_mfma_f32_32x32x16_bf16 v[66:81], v[192:195], v[138:141], v[66:81]
	v_mfma_f32_32x32x16_bf16 v[34:49], v[192:195], v[168:171], v[34:49]
	v_mfma_f32_32x32x16_bf16 v[66:81], v[196:199], v[142:145], v[66:81]
	v_mfma_f32_32x32x16_bf16 v[34:49], v[196:199], v[172:175], v[34:49]
	v_mfma_f32_32x32x16_bf16 v[18:33], v[200:203], v[130:133], v[18:33]
	v_mfma_f32_32x32x16_bf16 v[2:17], v[200:203], v[146:149], v[2:17]
	v_mfma_f32_32x32x16_bf16 v[18:33], v[228:231], v[134:137], v[18:33]
	v_mfma_f32_32x32x16_bf16 v[2:17], v[228:231], v[150:153], v[2:17]
	v_mfma_f32_32x32x16_bf16 v[18:33], v[232:235], v[138:141], v[18:33]
	v_mfma_f32_32x32x16_bf16 v[2:17], v[232:235], v[168:171], v[2:17]
	v_mfma_f32_32x32x16_bf16 v[18:33], v[236:239], v[142:145], v[18:33]
	v_mfma_f32_32x32x16_bf16 v[2:17], v[236:239], v[172:175], v[2:17]
	s_barrier
	s_cmp_eq_u32 s101, 0
	s_cbranch_scc0 .Lg8_ia_p1
	s_barrier

; template <bool SWAP>
; DI void gemm_mainloop(f32x16 (&acc)[4][2], const u16* __restrict__ A, int lda, int rlo, int rhi,
;                       const u16* __restrict__ B, int ldb, int K, char* lds, const u16* zero_line) {
;     ...
; #pragma unroll 2
;   for (int kt = 0; kt < nk; ++kt) {
;     const char* st = lds + (kt & 1) * 65536;
;     ldfrag(st, 0, 0);
;     mma(1);
;     pat_rd();
;     if (kt + 1 < nk) glds(kt + 1, (kt + 1) & 1);
;     ldfrag(st, 1, 1);
;     mma(0);
;     pat_rd();
;     ldfrag(st, 2, 0);
;     mma(1);
;     pat_rd();
;     ldfrag(st, 3, 1);
;     mma(0);
;     pat_rd();
;     asm volatile("s_waitcnt vmcnt(0)" ::: "memory");
;     __syncthreads();
;   }
.Lg8_ib:
	v_add3_u32 v187, v166, v161, 0
	v_add3_u32 v248, v166, v163, 0
	ds_read_b128 v[130:133], v187
	ds_read_b128 v[134:137], v248
	ds_read_b128 v[146:149], v187 offset:4096
	ds_read_b128 v[150:153], v248 offset:4096
	v_add3_u32 v187, v166, v164, 0
	v_add3_u32 v248, v166, v165, 0
	ds_read_b128 v[138:141], v187
	ds_read_b128 v[142:145], v248
	ds_read_b128 v[168:171], v187 offset:4096
	ds_read_b128 v[172:175], v248 offset:4096
	s_add_u32 m0, s100, 0x14000
	s_nop 0
	global_load_lds_dwordx4 v241, s[6:7]
	v_add_u32_e32 v241, 0x80, v241
	s_add_u32 m0, s100, 0x16000
	s_nop 0
	global_load_lds_dwordx4 v243, s[6:7]
	v_add_u32_e32 v243, 0x80, v243
	s_barrier
	s_waitcnt lgkmcnt(0)
	v_mfma_f32_32x32x16_bf16 v[114:129], v[130:133], v[176:179], v[114:129]
	v_mfma_f32_32x32x16_bf16 v[98:113], v[146:149], v[176:179], v[98:113]
	v_mfma_f32_32x32x16_bf16 v[114:129], v[134:137], v[180:183], v[114:129]
	v_mfma_f32_32x32x16_bf16 v[98:113], v[150:153], v[180:183], v[98:113]
	v_mfma_f32_32x32x16_bf16 v[114:129], v[138:141], v[192:195], v[114:129]
	v_mfma_f32_32x32x16_bf16 v[98:113], v[168:171], v[192:195], v[98:113]
	v_mfma_f32_32x32x16_bf16 v[114:129], v[142:145], v[196:199], v[114:129]
	v_mfma_f32_32x32x16_bf16 v[98:113], v[172:175], v[196:199], v[98:113]
	s_barrier
	v_add3_u32 v187, v186, v161, 0
	v_add3_u32 v248, v186, v163, 0
	ds_read_b128 v[200:203], v187 offset:49152
	ds_read_b128 v[228:231], v248 offset:49152
	v_add3_u32 v187, v186, v164, 0
	v_add3_u32 v248, v186, v165, 0
	ds_read_b128 v[232:235], v187 offset:49152
	ds_read_b128 v[236:239], v248 offset:49152
	s_add_u32 m0, s100, 0x8000
	s_nop 0
	global_load_lds_dwordx4 v244, s[8:9]
	v_add_u32_e32 v244, 0x80, v244
	s_add_u32 m0, s100, 0xa000
	s_nop 0
	global_load_lds_dwordx4 v246, s[8:9]
	v_add_u32_e32 v246, 0x80, v246
	s_barrier
	s_waitcnt lgkmcnt(0)
	v_mfma_f32_32x32x16_bf16 v[82:97], v[130:133], v[200:203], v[82:97]
	v_mfma_f32_32x32x16_bf16 v[50:65], v[146:149], v[200:203], v[50:65]
	v_mfma_f32_32x32x16_bf16 v[82:97], v[134:137], v[228:231], v[82:97]
	v_mfma_f32_32x32x16_bf16 v[50:65], v[150:153], v[228:231], v[50:65]
	v_mfma_f32_32x32x16_bf16 v[82:97], v[138:141], v[232:235], v[82:97]
	v_mfma_f32_32x32x16_bf16 v[50:65], v[168:171], v[232:235], v[50:65]
	v_mfma_f32_32x32x16_bf16 v[82:97], v[142:145], v[236:239], v[82:97]
	v_mfma_f32_32x32x16_bf16 v[50:65], v[172:175], v[236:239], v[50:65]
	s_barrier
	v_add3_u32 v187, v166, v161, 0
	v_add3_u32 v248, v166, v163, 0
	ds_read_b128 v[130:133], v187 offset:16384
	ds_read_b128 v[134:137], v248 offset:16384
	ds_read_b128 v[146:149], v187 offset:20480
	ds_read_b128 v[150:153], v248 offset:20480
	v_add3_u32 v187, v166, v164, 0
	v_add3_u32 v248, v166, v165, 0
	ds_read_b128 v[138:141], v187 offset:16384
	ds_read_b128 v[142:145], v248 offset:16384
	ds_read_b128 v[168:171], v187 offset:20480
	ds_read_b128 v[172:175], v248 offset:20480
	s_add_u32 m0, s100, 0x0
	s_nop 0
	global_load_lds_dwordx4 v240, s[6:7]
	v_add_u32_e32 v240, 0x80, v240
	s_add_u32 m0, s100, 0x2000
	s_nop 0
	global_load_lds_dwordx4 v242, s[6:7]
	v_add_u32_e32 v242, 0x80, v242
	s_waitcnt vmcnt(10)
	s_barrier
	s_waitcnt lgkmcnt(0)
	v_mfma_f32_32x32x16_bf16 v[66:81], v[130:133], v[176:179], v[66:81]
	v_mfma_f32_32x32x16_bf16 v[34:49], v[146:149], v[176:179], v[34:49]
	v_mfma_f32_32x32x16_bf16 v[66:81], v[134:137], v[180:183], v[66:81]
	v_mfma_f32_32x32x16_bf16 v[34:49], v[150:153], v[180:183], v[34:49]
	v_mfma_f32_32x32x16_bf16 v[66:81], v[138:141], v[192:195], v[66:81]
	v_mfma_f32_32x32x16_bf16 v[34:49], v[168:171], v[192:195], v[34:49]
	v_mfma_f32_32x32x16_bf16 v[66:81], v[142:145], v[196:199], v[66:81]
	v_mfma_f32_32x32x16_bf16 v[34:49], v[172:175], v[196:199], v[34:49]
	s_barrier
	v_add3_u32 v187, v186, v161, s10
	v_add3_u32 v248, v186, v163, s10
	ds_read_b128 v[176:179], v187 offset:32768
	ds_read_b128 v[180:183], v248 offset:32768
	v_add3_u32 v187, v186, v164, s10
	v_add3_u32 v248, v186, v165, s10
	ds_read_b128 v[192:195], v187 offset:32768
	ds_read_b128 v[196:199], v248 offset:32768
	s_add_u32 m0, s100, 0xc000
	s_nop 0
	global_load_lds_dwordx4 v245, s[8:9]
	v_add_u32_e32 v245, 0x80, v245
	s_add_u32 m0, s100, 0xe000
	s_nop 0
	global_load_lds_dwordx4 v247, s[8:9]
	v_add_u32_e32 v247, 0x80, v247
	s_waitcnt vmcnt(6)
	s_barrier
	s_waitcnt lgkmcnt(0)
	v_mfma_f32_32x32x16_bf16 v[18:33], v[130:133], v[200:203], v[18:33]
	v_mfma_f32_32x32x16_bf16 v[2:17], v[146:149], v[200:203], v[2:17]
	v_mfma_f32_32x32x16_bf16 v[18:33], v[134:137], v[228:231], v[18:33]
	v_mfma_f32_32x32x16_bf16 v[2:17], v[150:153], v[228:231], v[2:17]
	v_mfma_f32_32x32x16_bf16 v[18:33], v[138:141], v[232:235], v[18:33]
	v_mfma_f32_32x32x16_bf16 v[2:17], v[168:171], v[232:235], v[2:17]
	v_mfma_f32_32x32x16_bf16 v[18:33], v[142:145], v[236:239], v[18:33]
	v_mfma_f32_32x32x16_bf16 v[2:17], v[172:175], v[236:239], v[2:17]
	s_barrier
	v_add3_u32 v187, v166, v161, s10
	v_add3_u32 v248, v166, v163, s10
	ds_read_b128 v[130:133], v187
	ds_read_b128 v[134:137], v248
	ds_read_b128 v[146:149], v187 offset:4096
	ds_read_b128 v[150:153], v248 offset:4096
	v_add3_u32 v187, v166, v164, s10
	v_add3_u32 v248, v166, v165, s10
	ds_read_b128 v[138:141], v187
	ds_read_b128 v[142:145], v248
	ds_read_b128 v[168:171], v187 offset:4096
	ds_read_b128 v[172:175], v248 offset:4096
	s_add_u32 m0, s100, 0x4000
	s_nop 0
	global_load_lds_dwordx4 v241, s[6:7]
	v_add_u32_e32 v241, 0x80, v241
	s_add_u32 m0, s100, 0x6000
	s_nop 0
	global_load_lds_dwordx4 v243, s[6:7]
	v_add_u32_e32 v243, 0x80, v243
	s_barrier
; template <bool SWAP>
; DI void gemm_mainloop(f32x16 (&acc)[4][2], const u16* __restrict__ A, int lda, int rlo, int rhi,
;                       const u16* __restrict__ B, int ldb, int K, char* lds, const u16* zero_line) {
;     ...
; #pragma unroll 2
;   for (int kt = 0; kt < nk; ++kt) {
;     const char* st = lds + (kt & 1) * 65536;
;     ldfrag(st, 0, 0);
;     mma(1);
;     pat_rd();
;     if (kt + 1 < nk) glds(kt + 1, (kt + 1) & 1);
;     ldfrag(st, 1, 1);
;     mma(0);
;     pat_rd();
;     ldfrag(st, 2, 0);
;     mma(1);
;     pat_rd();
;     ldfrag(st, 3, 1);
;     mma(0);
;     pat_rd();
;     asm volatile("s_waitcnt vmcnt(0)" ::: "memory");
;     __syncthreads();
;   }
	s_waitcnt lgkmcnt(0)
	v_mfma_f32_32x32x16_bf16 v[114:129], v[130:133], v[176:179], v[114:129]
	v_mfma_f32_32x32x16_bf16 v[98:113], v[146:149], v[176:179], v[98:113]
	v_mfma_f32_32x32x16_bf16 v[114:129], v[134:137], v[180:183], v[114:129]
	v_mfma_f32_32x32x16_bf16 v[98:113], v[150:153], v[180:183], v[98:113]
	v_mfma_f32_32x32x16_bf16 v[114:129], v[138:141], v[192:195], v[114:129]
	v_mfma_f32_32x32x16_bf16 v[98:113], v[168:171], v[192:195], v[98:113]
	v_mfma_f32_32x32x16_bf16 v[114:129], v[142:145], v[196:199], v[114:129]
	v_mfma_f32_32x32x16_bf16 v[98:113], v[172:175], v[196:199], v[98:113]
	s_barrier
	v_add3_u32 v187, v186, v161, s10
	v_add3_u32 v248, v186, v163, s10
	ds_read_b128 v[200:203], v187 offset:49152
	ds_read_b128 v[228:231], v248 offset:49152
	v_add3_u32 v187, v186, v164, s10
	v_add3_u32 v248, v186, v165, s10
	ds_read_b128 v[232:235], v187 offset:49152
	ds_read_b128 v[236:239], v248 offset:49152
	s_add_u32 m0, s100, 0x18000
	s_nop 0
	global_load_lds_dwordx4 v244, s[8:9]
	v_add_u32_e32 v244, 0x80, v244
	s_add_u32 m0, s100, 0x1a000
	s_nop 0
	global_load_lds_dwordx4 v246, s[8:9]
	v_add_u32_e32 v246, 0x80, v246
	s_barrier
	s_waitcnt lgkmcnt(0)
	v_mfma_f32_32x32x16_bf16 v[82:97], v[130:133], v[200:203], v[82:97]
	v_mfma_f32_32x32x16_bf16 v[50:65], v[146:149], v[200:203], v[50:65]
	v_mfma_f32_32x32x16_bf16 v[82:97], v[134:137], v[228:231], v[82:97]
	v_mfma_f32_32x32x16_bf16 v[50:65], v[150:153], v[228:231], v[50:65]
	v_mfma_f32_32x32x16_bf16 v[82:97], v[138:141], v[232:235], v[82:97]
	v_mfma_f32_32x32x16_bf16 v[50:65], v[168:171], v[232:235], v[50:65]
	v_mfma_f32_32x32x16_bf16 v[82:97], v[142:145], v[236:239], v[82:97]
	v_mfma_f32_32x32x16_bf16 v[50:65], v[172:175], v[236:239], v[50:65]
	s_barrier
	v_add3_u32 v187, v166, v161, s10
	v_add3_u32 v248, v166, v163, s10
	ds_read_b128 v[130:133], v187 offset:16384
	ds_read_b128 v[134:137], v248 offset:16384
	ds_read_b128 v[146:149], v187 offset:20480
	ds_read_b128 v[150:153], v248 offset:20480
	v_add3_u32 v187, v166, v164, s10
	v_add3_u32 v248, v166, v165, s10
	ds_read_b128 v[138:141], v187 offset:16384
	ds_read_b128 v[142:145], v248 offset:16384
	ds_read_b128 v[168:171], v187 offset:20480
	ds_read_b128 v[172:175], v248 offset:20480
	s_add_u32 m0, s100, 0x10000
	s_nop 0
	global_load_lds_dwordx4 v240, s[6:7]
	v_add_u32_e32 v240, 0x80, v240
	s_add_u32 m0, s100, 0x12000
	s_nop 0
	global_load_lds_dwordx4 v242, s[6:7]
	v_add_u32_e32 v242, 0x80, v242
	s_waitcnt vmcnt(10)
	s_barrier
	s_waitcnt lgkmcnt(0)
	v_mfma_f32_32x32x16_bf16 v[66:81], v[130:133], v[176:179], v[66:81]
	v_mfma_f32_32x32x16_bf16 v[34:49], v[146:149], v[176:179], v[34:49]
	v_mfma_f32_32x32x16_bf16 v[66:81], v[134:137], v[180:183], v[66:81]
	v_mfma_f32_32x32x16_bf16 v[34:49], v[150:153], v[180:183], v[34:49]
	v_mfma_f32_32x32x16_bf16 v[66:81], v[138:141], v[192:195], v[66:81]
	v_mfma_f32_32x32x16_bf16 v[34:49], v[168:171], v[192:195], v[34:49]
	v_mfma_f32_32x32x16_bf16 v[66:81], v[142:145], v[196:199], v[66:81]
	v_mfma_f32_32x32x16_bf16 v[34:49], v[172:175], v[196:199], v[34:49]
	s_barrier
	v_add3_u32 v187, v186, v161, 0
	v_add3_u32 v248, v186, v163, 0
	ds_read_b128 v[176:179], v187 offset:32768
	ds_read_b128 v[180:183], v248 offset:32768
	v_add3_u32 v187, v186, v164, 0
	v_add3_u32 v248, v186, v165, 0
	ds_read_b128 v[192:195], v187 offset:32768
	ds_read_b128 v[196:199], v248 offset:32768
	s_add_u32 m0, s100, 0x1c000
	s_nop 0
	global_load_lds_dwordx4 v245, s[8:9]
	v_add_u32_e32 v245, 0x80, v245
	s_add_u32 m0, s100, 0x1e000
	s_nop 0
	global_load_lds_dwordx4 v247, s[8:9]
	v_add_u32_e32 v247, 0x80, v247
	s_waitcnt vmcnt(6)
	s_barrier
	s_waitcnt lgkmcnt(0)
	v_mfma_f32_32x32x16_bf16 v[18:33], v[130:133], v[200:203], v[18:33]
	v_mfma_f32_32x32x16_bf16 v[2:17], v[146:149], v[200:203], v[2:17]
	v_mfma_f32_32x32x16_bf16 v[18:33], v[134:137], v[228:231], v[18:33]
	v_mfma_f32_32x32x16_bf16 v[2:17], v[150:153], v[228:231], v[2:17]
	v_mfma_f32_32x32x16_bf16 v[18:33], v[138:141], v[232:235], v[18:33]
	v_mfma_f32_32x32x16_bf16 v[2:17], v[168:171], v[232:235], v[2:17]
	v_mfma_f32_32x32x16_bf16 v[18:33], v[142:145], v[236:239], v[18:33]
	v_mfma_f32_32x32x16_bf16 v[2:17], v[172:175], v[236:239], v[2:17]
	s_barrier
	s_add_i32 s11, s11, 2
	s_cmp_lt_u32 s11, 14
	s_cbranch_scc1 .Lg8_ib
	v_add3_u32 v187, v166, v161, 0
	v_add3_u32 v248, v166, v163, 0
	ds_read_b128 v[130:133], v187
	ds_read_b128 v[134:137], v248
	ds_read_b128 v[146:149], v187 offset:4096
	ds_read_b128 v[150:153], v248 offset:4096
	v_add3_u32 v187, v166, v164, 0
	v_add3_u32 v248, v166, v165, 0
	ds_read_b128 v[138:141], v187
	ds_read_b128 v[142:145], v248
	ds_read_b128 v[168:171], v187 offset:4096
	ds_read_b128 v[172:175], v248 offset:4096
	s_add_u32 m0, s100, 0x14000
	s_nop 0
	global_load_lds_dwordx4 v241, s[6:7]
	v_add_u32_e32 v241, 0x80, v241
	s_add_u32 m0, s100, 0x16000
	s_nop 0
	global_load_lds_dwordx4 v243, s[6:7]
	v_add_u32_e32 v243, 0x80, v243
	s_barrier
	s_waitcnt lgkmcnt(0)
	v_mfma_f32_32x32x16_bf16 v[114:129], v[130:133], v[176:179], v[114:129]
	v_mfma_f32_32x32x16_bf16 v[98:113], v[146:149], v[176:179], v[98:113]
	v_mfma_f32_32x32x16_bf16 v[114:129], v[134:137], v[180:183], v[114:129]
	v_mfma_f32_32x32x16_bf16 v[98:113], v[150:153], v[180:183], v[98:113]
	v_mfma_f32_32x32x16_bf16 v[114:129], v[138:141], v[192:195], v[114:129]
	v_mfma_f32_32x32x16_bf16 v[98:113], v[168:171], v[192:195], v[98:113]
	v_mfma_f32_32x32x16_bf16 v[114:129], v[142:145], v[196:199], v[114:129]
	v_mfma_f32_32x32x16_bf16 v[98:113], v[172:175], v[196:199], v[98:113]
	s_barrier
; template <bool SWAP>
; DI void gemm_mainloop(f32x16 (&acc)[4][2], const u16* __restrict__ A, int lda, int rlo, int rhi,
;                       const u16* __restrict__ B, int ldb, int K, char* lds, const u16* zero_line) {
;     ...
;   for (int kt = 0; kt < nk; ++kt) {
;     const char* st = lds + (kt & 1) * 65536;
;     ldfrag(st, 0, 0);
;     mma(1);
;     pat_rd();
;     if (kt + 1 < nk) glds(kt + 1, (kt + 1) & 1);
;     ldfrag(st, 1, 1);
;     mma(0);
;     pat_rd();
;     ldfrag(st, 2, 0);
;     mma(1);
;     pat_rd();
;     ldfrag(st, 3, 1);
;     mma(0);
;     pat_rd();
;     asm volatile("s_waitcnt vmcnt(0)" ::: "memory");
;     __syncthreads();
;   }
;   mma(1);
	v_add3_u32 v187, v186, v161, 0
	v_add3_u32 v248, v186, v163, 0
	ds_read_b128 v[200:203], v187 offset:49152
	ds_read_b128 v[228:231], v248 offset:49152
	v_add3_u32 v187, v186, v164, 0
	v_add3_u32 v248, v186, v165, 0
	ds_read_b128 v[232:235], v187 offset:49152
	ds_read_b128 v[236:239], v248 offset:49152
	s_barrier
	s_waitcnt lgkmcnt(0)
	v_mfma_f32_32x32x16_bf16 v[82:97], v[130:133], v[200:203], v[82:97]
	v_mfma_f32_32x32x16_bf16 v[50:65], v[146:149], v[200:203], v[50:65]
	v_mfma_f32_32x32x16_bf16 v[82:97], v[134:137], v[228:231], v[82:97]
	v_mfma_f32_32x32x16_bf16 v[50:65], v[150:153], v[228:231], v[50:65]
	v_mfma_f32_32x32x16_bf16 v[82:97], v[138:141], v[232:235], v[82:97]
	v_mfma_f32_32x32x16_bf16 v[50:65], v[168:171], v[232:235], v[50:65]
	v_mfma_f32_32x32x16_bf16 v[82:97], v[142:145], v[236:239], v[82:97]
	v_mfma_f32_32x32x16_bf16 v[50:65], v[172:175], v[236:239], v[50:65]
	s_barrier
	v_add3_u32 v187, v166, v161, 0
	v_add3_u32 v248, v166, v163, 0
	ds_read_b128 v[130:133], v187 offset:16384
	ds_read_b128 v[134:137], v248 offset:16384
	ds_read_b128 v[146:149], v187 offset:20480
	ds_read_b128 v[150:153], v248 offset:20480
	v_add3_u32 v187, v166, v164, 0
	v_add3_u32 v248, v166, v165, 0
	ds_read_b128 v[138:141], v187 offset:16384
	ds_read_b128 v[142:145], v248 offset:16384
	ds_read_b128 v[168:171], v187 offset:20480
	ds_read_b128 v[172:175], v248 offset:20480
	s_waitcnt vmcnt(4)
	s_barrier
	s_waitcnt lgkmcnt(0)
	v_mfma_f32_32x32x16_bf16 v[66:81], v[130:133], v[176:179], v[66:81]
	v_mfma_f32_32x32x16_bf16 v[34:49], v[146:149], v[176:179], v[34:49]
	v_mfma_f32_32x32x16_bf16 v[66:81], v[134:137], v[180:183], v[66:81]
	v_mfma_f32_32x32x16_bf16 v[34:49], v[150:153], v[180:183], v[34:49]
	v_mfma_f32_32x32x16_bf16 v[66:81], v[138:141], v[192:195], v[66:81]
	v_mfma_f32_32x32x16_bf16 v[34:49], v[168:171], v[192:195], v[34:49]
	v_mfma_f32_32x32x16_bf16 v[66:81], v[142:145], v[196:199], v[66:81]
	v_mfma_f32_32x32x16_bf16 v[34:49], v[172:175], v[196:199], v[34:49]
	v_mfma_f32_32x32x16_bf16 v[18:33], v[130:133], v[200:203], v[18:33]
	v_mfma_f32_32x32x16_bf16 v[2:17], v[146:149], v[200:203], v[2:17]
	v_mfma_f32_32x32x16_bf16 v[18:33], v[134:137], v[228:231], v[18:33]
	v_mfma_f32_32x32x16_bf16 v[2:17], v[150:153], v[228:231], v[2:17]
	v_mfma_f32_32x32x16_bf16 v[18:33], v[138:141], v[232:235], v[18:33]
	v_mfma_f32_32x32x16_bf16 v[2:17], v[168:171], v[232:235], v[2:17]
	v_mfma_f32_32x32x16_bf16 v[18:33], v[142:145], v[236:239], v[18:33]
	v_mfma_f32_32x32x16_bf16 v[2:17], v[172:175], v[236:239], v[2:17]
	s_barrier
	v_add3_u32 v187, v186, v161, s10
	v_add3_u32 v248, v186, v163, s10
	ds_read_b128 v[176:179], v187 offset:32768
	ds_read_b128 v[180:183], v248 offset:32768
	v_add3_u32 v187, v186, v164, s10
	v_add3_u32 v248, v186, v165, s10
	ds_read_b128 v[192:195], v187 offset:32768
	ds_read_b128 v[196:199], v248 offset:32768
	v_add3_u32 v187, v166, v161, s10
	v_add3_u32 v248, v166, v163, s10
	ds_read_b128 v[130:133], v187
	ds_read_b128 v[134:137], v248
	ds_read_b128 v[146:149], v187 offset:4096
	ds_read_b128 v[150:153], v248 offset:4096
	v_add3_u32 v187, v166, v164, s10
	v_add3_u32 v248, v166, v165, s10
	ds_read_b128 v[138:141], v187
	ds_read_b128 v[142:145], v248
	ds_read_b128 v[168:171], v187 offset:4096
	ds_read_b128 v[172:175], v248 offset:4096
	s_waitcnt vmcnt(2)
	s_barrier
	s_waitcnt lgkmcnt(0)
	v_mfma_f32_32x32x16_bf16 v[114:129], v[130:133], v[176:179], v[114:129]
	v_mfma_f32_32x32x16_bf16 v[98:113], v[146:149], v[176:179], v[98:113]
	v_mfma_f32_32x32x16_bf16 v[114:129], v[134:137], v[180:183], v[114:129]
	v_mfma_f32_32x32x16_bf16 v[98:113], v[150:153], v[180:183], v[98:113]
	v_mfma_f32_32x32x16_bf16 v[114:129], v[138:141], v[192:195], v[114:129]
	v_mfma_f32_32x32x16_bf16 v[98:113], v[168:171], v[192:195], v[98:113]
	v_mfma_f32_32x32x16_bf16 v[114:129], v[142:145], v[196:199], v[114:129]
	v_mfma_f32_32x32x16_bf16 v[98:113], v[172:175], v[196:199], v[98:113]
	s_barrier
	v_add3_u32 v187, v186, v161, s10
	v_add3_u32 v248, v186, v163, s10
	ds_read_b128 v[200:203], v187 offset:49152
	ds_read_b128 v[228:231], v248 offset:49152
	v_add3_u32 v187, v186, v164, s10
	v_add3_u32 v248, v186, v165, s10
	ds_read_b128 v[232:235], v187 offset:49152
	ds_read_b128 v[236:239], v248 offset:49152
	s_waitcnt vmcnt(0)
	s_barrier
	s_waitcnt lgkmcnt(0)
	v_mfma_f32_32x32x16_bf16 v[82:97], v[130:133], v[200:203], v[82:97]
	v_mfma_f32_32x32x16_bf16 v[50:65], v[146:149], v[200:203], v[50:65]
	v_mfma_f32_32x32x16_bf16 v[82:97], v[134:137], v[228:231], v[82:97]
	v_mfma_f32_32x32x16_bf16 v[50:65], v[150:153], v[228:231], v[50:65]
	v_mfma_f32_32x32x16_bf16 v[82:97], v[138:141], v[232:235], v[82:97]
	v_mfma_f32_32x32x16_bf16 v[50:65], v[168:171], v[232:235], v[50:65]
	v_mfma_f32_32x32x16_bf16 v[82:97], v[142:145], v[236:239], v[82:97]
	v_mfma_f32_32x32x16_bf16 v[50:65], v[172:175], v[236:239], v[50:65]
	s_barrier
	v_add3_u32 v187, v166, v161, s10
	v_add3_u32 v248, v166, v163, s10
	ds_read_b128 v[130:133], v187 offset:16384
	ds_read_b128 v[134:137], v248 offset:16384
	ds_read_b128 v[146:149], v187 offset:20480
	ds_read_b128 v[150:153], v248 offset:20480
	v_add3_u32 v187, v166, v164, s10
	v_add3_u32 v248, v166, v165, s10
	ds_read_b128 v[138:141], v187 offset:16384
	ds_read_b128 v[142:145], v248 offset:16384
	ds_read_b128 v[168:171], v187 offset:20480
	ds_read_b128 v[172:175], v248 offset:20480
	s_barrier
	s_waitcnt lgkmcnt(0)
	v_mfma_f32_32x32x16_bf16 v[66:81], v[130:133], v[176:179], v[66:81]
	v_mfma_f32_32x32x16_bf16 v[34:49], v[146:149], v[176:179], v[34:49]
	v_mfma_f32_32x32x16_bf16 v[66:81], v[134:137], v[180:183], v[66:81]
	v_mfma_f32_32x32x16_bf16 v[34:49], v[150:153], v[180:183], v[34:49]
	v_mfma_f32_32x32x16_bf16 v[66:81], v[138:141], v[192:195], v[66:81]
	v_mfma_f32_32x32x16_bf16 v[34:49], v[168:171], v[192:195], v[34:49]
	v_mfma_f32_32x32x16_bf16 v[66:81], v[142:145], v[196:199], v[66:81]
	v_mfma_f32_32x32x16_bf16 v[34:49], v[172:175], v[196:199], v[34:49]
	v_mfma_f32_32x32x16_bf16 v[18:33], v[130:133], v[200:203], v[18:33]
	v_mfma_f32_32x32x16_bf16 v[2:17], v[146:149], v[200:203], v[2:17]
	v_mfma_f32_32x32x16_bf16 v[18:33], v[134:137], v[228:231], v[18:33]
	v_mfma_f32_32x32x16_bf16 v[2:17], v[150:153], v[228:231], v[2:17]
	v_mfma_f32_32x32x16_bf16 v[18:33], v[138:141], v[232:235], v[18:33]
	v_mfma_f32_32x32x16_bf16 v[2:17], v[168:171], v[232:235], v[2:17]
	v_mfma_f32_32x32x16_bf16 v[18:33], v[142:145], v[236:239], v[18:33]
	v_mfma_f32_32x32x16_bf16 v[2:17], v[172:175], v[236:239], v[2:17]
	s_barrier
	s_cmp_eq_u32 s101, 0
	s_cbranch_scc0 .Lg8_ib_p1
	s_barrier
